# keep_v2 + drop dead zero-fills of the deferred prep unpack targets + hoist gc LDS reads out of the per-element branches in the A^T and Gram strips
# speedup vs baseline: 1.0079x; 1.0079x over previous
; #define GAS __attribute__((address_space(1)))
; __device__ __forceinline__ void prep_seg(const bf16_t* QK, const float* cw, const size_t rowbase, const int t0, const int h, const int seg, const int lane, float (&o)[8][8]) {
;     const int rg = lane >> 3, cg = lane & 7, col = seg * 512 + h * 64 + cg * 8;
;     float wt[4][8];
; #pragma unroll
;     for (int j = 0; j < 4; ++j) { const f32x4 a = *(const GAS f32x4*)(cw + j * CONVD + col), b = *(const GAS f32x4*)(cw + j * CONVD + col + 4); wt[j][0] = a.x; wt[j][1] = a.y; wt[j][2] = a.z; wt[j][3] = a.w; wt[j][4] = b.x; wt[j][5] = b.y; wt[j][6] = b.z; wt[j][7] = b.w; }
; #pragma unroll
;     for (int r = 0; r < 8; ++r)
; #pragma unroll
;         for (int e = 0; e < 8; ++e) o[r][e] = 0.f;
; #pragma unroll
;     for (int rr = 0; rr < 11; ++rr) { const int t = t0 + 8 * rg + rr - 3; float x[8];
;         if (t >= 0) unpack8(*(const GAS v4u*)(QK + (rowbase + t) * CONVD + col), x); else {
; __device__ __forceinline__ void intra_item(Frame& F, const int item, LAS unsigned char* SA, LAS unsigned char* SB, LAS float* GC, LAS float* BT) {
;     ...
;     const float gl = GC[63];
;     float o[8][8];
;     prep_seg(QK, cw, rowbase, t0, h, 1, lane, o);
.LBB0_908:
	s_or_b64 exec, exec, s[0:1]
	s_lshl_b32 s0, s3, 6
	v_lshlrev_b32_e32 v172, 3, v88
	v_and_or_b32 v89, v172, 56, s0
	v_lshlrev_b32_e32 v64, 2, v89
	v_lshl_add_u64 v[34:35], s[70:71], 0, v[64:65]
	v_add_co_u32_e32 v2, vcc, 0x2000, v34
	s_mov_b64 s[0:1], 0x2000
	s_nop 0
	v_addc_co_u32_e32 v3, vcc, 0, v35, vcc
	global_load_dwordx4 v[8:11], v64, s[70:71] offset:2064
	global_load_dwordx4 v[20:23], v64, s[70:71] offset:2048
	v_lshl_add_u64 v[0:1], v[34:35], 0, s[0:1]
	global_load_dwordx4 v[16:19], v[2:3], off
	global_load_dwordx4 v[12:15], v[0:1], off offset:16
	s_mov_b64 s[0:1], 0x3800
	v_add_co_u32_e32 v2, vcc, 0x3000, v34
	v_lshl_add_u64 v[0:1], v[34:35], 0, s[0:1]
	s_nop 0
	v_addc_co_u32_e32 v3, vcc, 0, v35, vcc
	global_load_dwordx4 v[28:31], v[2:3], off offset:2048
	global_load_dwordx4 v[24:27], v[0:1], off offset:16
	s_mov_b64 s[0:1], 0x5000
	v_add_co_u32_e32 v0, vcc, 0x5000, v34
	v_lshl_add_u64 v[4:5], v[34:35], 0, s[0:1]
	s_nop 0
	v_addc_co_u32_e32 v1, vcc, 0, v35, vcc
	global_load_dwordx4 v[0:3], v[0:1], off
	s_nop 0
	global_load_dwordx4 v[4:7], v[4:5], off offset:16
	ds_read_b32 v33, v210 offset:18684
	v_and_b32_e32 v158, -8, v88
	v_or_b32_e32 v32, 0x200, v89
	v_add_u32_e32 v66, s2, v158
	v_cmp_lt_i32_e64 s[0:1], 2, v66

; #define GAS __attribute__((address_space(1)))
; __device__ __forceinline__ void prep_seg(const bf16_t* QK, const float* cw, const size_t rowbase, const int t0, const int h, const int seg, const int lane, float (&o)[8][8]) {
;     ...
;     for (int rr = 0; rr < 11; ++rr) { const int t = t0 + 8 * rg + rr - 3; float x[8];
;         if (t >= 0) unpack8(*(const GAS v4u*)(QK + (rowbase + t) * CONVD + col), x); else {
; #pragma unroll
;             for (int e = 0; e < 8; ++e) x[e] = 0.f; }
	v_add_u32_e32 v68, -3, v66
	v_lshlrev_b32_e32 v64, 1, v32


; #define GAS __attribute__((address_space(1)))
; __device__ __forceinline__ void prep_seg(const bf16_t* QK, const float* cw, const size_t rowbase, const int t0, const int h, const int seg, const int lane, float (&o)[8][8]) {
;     ...
;     for (int rr = 0; rr < 11; ++rr) { const int t = t0 + 8 * rg + rr - 3; float x[8];
;         if (t >= 0) unpack8(*(const GAS v4u*)(QK + (rowbase + t) * CONVD + col), x); else {
; #pragma unroll
;             for (int e = 0; e < 8; ++e) x[e] = 0.f; }
	v_mov_b32_e32 v196, 0
	v_mov_b32_e32 v197, 0
	v_mov_b32_e32 v198, 0
	v_mov_b32_e32 v199, 0
	s_and_saveexec_b64 s[2:3], s[0:1]
	v_mov_b32_e32 v69, v65
	v_lshl_add_u64 v[36:37], s[82:83], 0, v[68:69]
	v_mov_b64_e32 v[38:39], s[46:47]
	v_mad_u64_u32 v[38:39], s[4:5], v36, s72, v[38:39]
	v_mad_i32_i24 v39, v37, s72, v39
	v_lshl_add_u64 v[36:37], v[38:39], 0, v[64:65]
	global_load_dwordx4 v[196:199], v[36:37], off
.LBB0_910:
	s_or_b64 exec, exec, s[2:3]
	v_cmp_lt_i32_e64 s[2:3], 1, v66
	v_add_u32_e32 v70, -2, v66


; #define GAS __attribute__((address_space(1)))
; __device__ __forceinline__ void prep_seg(const bf16_t* QK, const float* cw, const size_t rowbase, const int t0, const int h, const int seg, const int lane, float (&o)[8][8]) {
;     ...
;     for (int rr = 0; rr < 11; ++rr) { const int t = t0 + 8 * rg + rr - 3; float x[8];
;         if (t >= 0) unpack8(*(const GAS v4u*)(QK + (rowbase + t) * CONVD + col), x); else {
; #pragma unroll
;             for (int e = 0; e < 8; ++e) x[e] = 0.f; }
	v_mov_b32_e32 v204, 0
	v_mov_b32_e32 v205, 0
	v_mov_b32_e32 v206, 0
	v_mov_b32_e32 v207, 0
	s_and_saveexec_b64 s[4:5], s[2:3]
	v_mov_b32_e32 v71, v65
	v_lshl_add_u64 v[36:37], s[82:83], 0, v[70:71]
	v_mov_b64_e32 v[38:39], s[46:47]
	v_mad_u64_u32 v[38:39], s[6:7], v36, s72, v[38:39]
	v_mad_i32_i24 v39, v37, s72, v39
	v_lshl_add_u64 v[36:37], v[38:39], 0, v[64:65]
	global_load_dwordx4 v[204:207], v[36:37], off
.LBB0_912:
	s_or_b64 exec, exec, s[4:5]
	v_cmp_lt_i32_e64 s[4:5], 0, v66

; #define GAS __attribute__((address_space(1)))
; __device__ __forceinline__ void prep_seg(const bf16_t* QK, const float* cw, const size_t rowbase, const int t0, const int h, const int seg, const int lane, float (&o)[8][8]) {
;     ...
;     for (int rr = 0; rr < 11; ++rr) { const int t = t0 + 8 * rg + rr - 3; float x[8];
;         if (t >= 0) unpack8(*(const GAS v4u*)(QK + (rowbase + t) * CONVD + col), x); else {
; #pragma unroll
;             for (int e = 0; e < 8; ++e) x[e] = 0.f; }
	v_add_u32_e32 v72, -1, v66


; #define GAS __attribute__((address_space(1)))
; __device__ __forceinline__ void prep_seg(const bf16_t* QK, const float* cw, const size_t rowbase, const int t0, const int h, const int seg, const int lane, float (&o)[8][8]) {
;     ...
;     for (int rr = 0; rr < 11; ++rr) { const int t = t0 + 8 * rg + rr - 3; float x[8];
;         if (t >= 0) unpack8(*(const GAS v4u*)(QK + (rowbase + t) * CONVD + col), x); else {
; #pragma unroll
;             for (int e = 0; e < 8; ++e) x[e] = 0.f; }
	v_mov_b32_e32 v212, 0
	v_mov_b32_e32 v213, 0
	v_mov_b32_e32 v214, 0
	v_mov_b32_e32 v215, 0
	s_and_saveexec_b64 s[6:7], s[4:5]
	v_mov_b32_e32 v73, v65
	v_lshl_add_u64 v[36:37], s[82:83], 0, v[72:73]
	v_mov_b64_e32 v[38:39], s[46:47]
	v_mad_u64_u32 v[38:39], s[8:9], v36, s72, v[38:39]
	v_mad_i32_i24 v39, v37, s72, v39
	v_lshl_add_u64 v[36:37], v[38:39], 0, v[64:65]
	global_load_dwordx4 v[212:215], v[36:37], off
.LBB0_914:
	s_or_b64 exec, exec, s[6:7]
	v_cmp_lt_i32_e64 s[6:7], -1, v66


; #define GAS __attribute__((address_space(1)))
; __device__ __forceinline__ void prep_seg(const bf16_t* QK, const float* cw, const size_t rowbase, const int t0, const int h, const int seg, const int lane, float (&o)[8][8]) {
;     ...
;     for (int rr = 0; rr < 11; ++rr) { const int t = t0 + 8 * rg + rr - 3; float x[8];
;         if (t >= 0) unpack8(*(const GAS v4u*)(QK + (rowbase + t) * CONVD + col), x); else {
; #pragma unroll
;             for (int e = 0; e < 8; ++e) x[e] = 0.f; }
	v_mov_b32_e32 v216, 0
	v_mov_b32_e32 v217, 0
	v_mov_b32_e32 v218, 0
	v_mov_b32_e32 v219, 0
	s_and_saveexec_b64 s[8:9], s[6:7]
	v_mov_b32_e32 v67, v65
	v_lshl_add_u64 v[36:37], s[82:83], 0, v[66:67]
	v_mov_b64_e32 v[38:39], s[46:47]
	v_mad_u64_u32 v[38:39], s[10:11], v36, s72, v[38:39]
	v_mad_i32_i24 v39, v37, s72, v39
	v_lshl_add_u64 v[36:37], v[38:39], 0, v[64:65]
	global_load_dwordx4 v[216:219], v[36:37], off
.LBB0_916:
	s_or_b64 exec, exec, s[8:9]
	v_or_b32_e32 v74, 1, v66
	v_cmp_lt_i32_e64 s[8:9], -2, v66


; #define GAS __attribute__((address_space(1)))
; __device__ __forceinline__ void prep_seg(const bf16_t* QK, const float* cw, const size_t rowbase, const int t0, const int h, const int seg, const int lane, float (&o)[8][8]) {
;     ...
;     for (int rr = 0; rr < 11; ++rr) { const int t = t0 + 8 * rg + rr - 3; float x[8];
;         if (t >= 0) unpack8(*(const GAS v4u*)(QK + (rowbase + t) * CONVD + col), x); else {
; #pragma unroll
;             for (int e = 0; e < 8; ++e) x[e] = 0.f; }
	v_mov_b32_e32 v220, 0
	v_mov_b32_e32 v221, 0
	v_mov_b32_e32 v222, 0
	v_mov_b32_e32 v223, 0
	s_and_saveexec_b64 s[10:11], s[8:9]
	v_mov_b32_e32 v75, v65
	v_lshl_add_u64 v[36:37], s[82:83], 0, v[74:75]
	v_mov_b64_e32 v[38:39], s[46:47]
	v_mad_u64_u32 v[38:39], s[12:13], v36, s72, v[38:39]
	v_mad_i32_i24 v39, v37, s72, v39
	v_lshl_add_u64 v[36:37], v[38:39], 0, v[64:65]
	global_load_dwordx4 v[220:223], v[36:37], off
.LBB0_918:
	s_or_b64 exec, exec, s[10:11]
	v_or_b32_e32 v76, 2, v66
	v_cmp_lt_i32_e64 s[10:11], -3, v66


; #define GAS __attribute__((address_space(1)))
; __device__ __forceinline__ void prep_seg(const bf16_t* QK, const float* cw, const size_t rowbase, const int t0, const int h, const int seg, const int lane, float (&o)[8][8]) {
;     ...
;     for (int rr = 0; rr < 11; ++rr) { const int t = t0 + 8 * rg + rr - 3; float x[8];
;         if (t >= 0) unpack8(*(const GAS v4u*)(QK + (rowbase + t) * CONVD + col), x); else {
; #pragma unroll
;             for (int e = 0; e < 8; ++e) x[e] = 0.f; }
	v_mov_b32_e32 v224, 0
	v_mov_b32_e32 v225, 0
	v_mov_b32_e32 v226, 0
	v_mov_b32_e32 v227, 0
	s_and_saveexec_b64 s[12:13], s[10:11]
	v_mov_b32_e32 v77, v65
	v_lshl_add_u64 v[36:37], s[82:83], 0, v[76:77]
	v_mov_b64_e32 v[38:39], s[46:47]
	v_mad_u64_u32 v[38:39], s[14:15], v36, s72, v[38:39]
	v_mad_i32_i24 v39, v37, s72, v39
	v_lshl_add_u64 v[36:37], v[38:39], 0, v[64:65]
	global_load_dwordx4 v[224:227], v[36:37], off
.LBB0_920:
	s_or_b64 exec, exec, s[12:13]
	v_or_b32_e32 v78, 3, v66
	v_cmp_lt_i32_e64 s[12:13], -4, v66


; #define GAS __attribute__((address_space(1)))
; __device__ __forceinline__ void prep_seg(const bf16_t* QK, const float* cw, const size_t rowbase, const int t0, const int h, const int seg, const int lane, float (&o)[8][8]) {
;     ...
;     for (int rr = 0; rr < 11; ++rr) { const int t = t0 + 8 * rg + rr - 3; float x[8];
;         if (t >= 0) unpack8(*(const GAS v4u*)(QK + (rowbase + t) * CONVD + col), x); else {
; #pragma unroll
;             for (int e = 0; e < 8; ++e) x[e] = 0.f; }
	v_mov_b32_e32 v228, 0
	v_mov_b32_e32 v229, 0
	v_mov_b32_e32 v230, 0
	v_mov_b32_e32 v231, 0
	s_and_saveexec_b64 s[14:15], s[12:13]
	v_mov_b32_e32 v79, v65
	v_lshl_add_u64 v[36:37], s[82:83], 0, v[78:79]
	v_mov_b64_e32 v[38:39], s[46:47]
	v_mad_u64_u32 v[38:39], s[16:17], v36, s72, v[38:39]
	v_mad_i32_i24 v39, v37, s72, v39
	v_lshl_add_u64 v[36:37], v[38:39], 0, v[64:65]
	global_load_dwordx4 v[228:231], v[36:37], off
.LBB0_922:
	s_or_b64 exec, exec, s[14:15]
	v_or_b32_e32 v80, 4, v66
	v_cmp_lt_i32_e64 s[14:15], -5, v66


; #define GAS __attribute__((address_space(1)))
; __device__ __forceinline__ void prep_seg(const bf16_t* QK, const float* cw, const size_t rowbase, const int t0, const int h, const int seg, const int lane, float (&o)[8][8]) {
;     ...
;     for (int rr = 0; rr < 11; ++rr) { const int t = t0 + 8 * rg + rr - 3; float x[8];
;         if (t >= 0) unpack8(*(const GAS v4u*)(QK + (rowbase + t) * CONVD + col), x); else {
; #pragma unroll
;             for (int e = 0; e < 8; ++e) x[e] = 0.f; }
	v_mov_b32_e32 v232, 0
	v_mov_b32_e32 v233, 0
	v_mov_b32_e32 v234, 0
	v_mov_b32_e32 v235, 0
	s_and_saveexec_b64 s[16:17], s[14:15]
	v_mov_b32_e32 v81, v65
	v_lshl_add_u64 v[36:37], s[82:83], 0, v[80:81]
	v_mov_b64_e32 v[38:39], s[46:47]
	v_mad_u64_u32 v[38:39], s[18:19], v36, s72, v[38:39]
	v_mad_i32_i24 v39, v37, s72, v39
	v_lshl_add_u64 v[36:37], v[38:39], 0, v[64:65]
	global_load_dwordx4 v[232:235], v[36:37], off
.LBB0_924:
	s_or_b64 exec, exec, s[16:17]
	v_or_b32_e32 v82, 5, v66
	v_cmp_lt_i32_e64 s[16:17], -6, v66


; #define GAS __attribute__((address_space(1)))
; __device__ __forceinline__ void prep_seg(const bf16_t* QK, const float* cw, const size_t rowbase, const int t0, const int h, const int seg, const int lane, float (&o)[8][8]) {
;     ...
;     for (int rr = 0; rr < 11; ++rr) { const int t = t0 + 8 * rg + rr - 3; float x[8];
;         if (t >= 0) unpack8(*(const GAS v4u*)(QK + (rowbase + t) * CONVD + col), x); else {
; #pragma unroll
;             for (int e = 0; e < 8; ++e) x[e] = 0.f; }
	v_mov_b32_e32 v236, 0
	v_mov_b32_e32 v237, 0
	v_mov_b32_e32 v238, 0
	v_mov_b32_e32 v239, 0
	s_and_saveexec_b64 s[18:19], s[16:17]
	v_mov_b32_e32 v83, v65
	v_lshl_add_u64 v[36:37], s[82:83], 0, v[82:83]
	v_mov_b64_e32 v[38:39], s[46:47]
	v_mad_u64_u32 v[38:39], s[20:21], v36, s72, v[38:39]
	v_mad_i32_i24 v39, v37, s72, v39
	v_lshl_add_u64 v[36:37], v[38:39], 0, v[64:65]
	global_load_dwordx4 v[236:239], v[36:37], off
.LBB0_926:
	s_or_b64 exec, exec, s[18:19]
	v_or_b32_e32 v84, 6, v66
	v_cmp_lt_i32_e64 s[18:19], -7, v66


; #define GAS __attribute__((address_space(1)))
; __device__ __forceinline__ void prep_seg(const bf16_t* QK, const float* cw, const size_t rowbase, const int t0, const int h, const int seg, const int lane, float (&o)[8][8]) {
;     ...
;     for (int rr = 0; rr < 11; ++rr) { const int t = t0 + 8 * rg + rr - 3; float x[8];
;         if (t >= 0) unpack8(*(const GAS v4u*)(QK + (rowbase + t) * CONVD + col), x); else {
; #pragma unroll
;             for (int e = 0; e < 8; ++e) x[e] = 0.f; }
	v_mov_b32_e32 v240, 0
	v_mov_b32_e32 v241, 0
	v_mov_b32_e32 v242, 0
	v_mov_b32_e32 v243, 0
	s_and_saveexec_b64 s[20:21], s[18:19]
	v_mov_b32_e32 v85, v65
	v_lshl_add_u64 v[36:37], s[82:83], 0, v[84:85]
	v_mov_b64_e32 v[38:39], s[46:47]
	v_mad_u64_u32 v[38:39], s[22:23], v36, s72, v[38:39]
	v_mad_i32_i24 v39, v37, s72, v39
	v_lshl_add_u64 v[36:37], v[38:39], 0, v[64:65]
	global_load_dwordx4 v[240:243], v[36:37], off
.LBB0_928:
	s_or_b64 exec, exec, s[20:21]
	v_or_b32_e32 v86, 7, v66
	v_cmp_lt_i32_e64 s[20:21], -8, v66
	v_mov_b32_e32 v32, 0


; #define GAS __attribute__((address_space(1)))
; __device__ __forceinline__ void prep_seg(const bf16_t* QK, const float* cw, const size_t rowbase, const int t0, const int h, const int seg, const int lane, float (&o)[8][8]) {
;     ...
;     for (int rr = 0; rr < 11; ++rr) { const int t = t0 + 8 * rg + rr - 3; float x[8];
;         if (t >= 0) unpack8(*(const GAS v4u*)(QK + (rowbase + t) * CONVD + col), x); else {
; #pragma unroll
;             for (int e = 0; e < 8; ++e) x[e] = 0.f; }
; #pragma unroll
;         for (int j = 0; j < 4; ++j) { const int r = rr - j;
;             if (r >= 0 && r < 8) {
; #pragma unroll
;                 for (int e = 0; e < 8; ++e) o[r][e] += wt[j][e] * x[e]; } } }
	v_mov_b32_e32 v244, 0
	v_mov_b32_e32 v245, 0
	v_mov_b32_e32 v246, 0
	v_mov_b32_e32 v247, 0
	s_and_saveexec_b64 s[22:23], s[20:21]
	v_mov_b32_e32 v87, v65
	v_lshl_add_u64 v[36:37], s[82:83], 0, v[86:87]
	v_mov_b64_e32 v[38:39], s[46:47]
	v_mad_u64_u32 v[38:39], s[24:25], v36, s72, v[38:39]
	v_mad_i32_i24 v39, v37, s72, v39
	v_lshl_add_u64 v[36:37], v[38:39], 0, v[64:65]
	global_load_dwordx4 v[244:247], v[36:37], off
.LBB0_930:
	s_or_b64 exec, exec, s[22:23]
	s_waitcnt vmcnt(10)
	v_lshlrev_b32_e32 v62, 16, v196
	v_and_b32_e32 v63, 0xffff0000, v196
	v_lshlrev_b32_e32 v90, 16, v197
	v_and_b32_e32 v91, 0xffff0000, v197
	v_lshlrev_b32_e32 v92, 16, v198
	v_and_b32_e32 v93, 0xffff0000, v198
	v_lshlrev_b32_e32 v94, 16, v199
	v_and_b32_e32 v95, 0xffff0000, v199
	s_waitcnt vmcnt(9)
	v_lshlrev_b32_e32 v60, 16, v204
	v_and_b32_e32 v61, 0xffff0000, v204
	v_lshlrev_b32_e32 v96, 16, v205
	v_and_b32_e32 v97, 0xffff0000, v205
	v_lshlrev_b32_e32 v98, 16, v206
	v_and_b32_e32 v99, 0xffff0000, v206
	v_lshlrev_b32_e32 v100, 16, v207
	v_and_b32_e32 v101, 0xffff0000, v207
	s_waitcnt vmcnt(8)
	v_lshlrev_b32_e32 v104, 16, v212
	v_and_b32_e32 v105, 0xffff0000, v212
	v_lshlrev_b32_e32 v106, 16, v213
	v_and_b32_e32 v107, 0xffff0000, v213
	v_lshlrev_b32_e32 v108, 16, v214
	v_and_b32_e32 v109, 0xffff0000, v214
	v_lshlrev_b32_e32 v110, 16, v215
	v_and_b32_e32 v111, 0xffff0000, v215
	s_waitcnt vmcnt(7)
	v_lshlrev_b32_e32 v102, 16, v216
	v_and_b32_e32 v103, 0xffff0000, v216
	v_lshlrev_b32_e32 v122, 16, v217
	v_and_b32_e32 v123, 0xffff0000, v217
	v_lshlrev_b32_e32 v124, 16, v218
	v_and_b32_e32 v125, 0xffff0000, v218
	v_lshlrev_b32_e32 v118, 16, v219
	v_and_b32_e32 v119, 0xffff0000, v219
	s_waitcnt vmcnt(6)
	v_lshlrev_b32_e32 v130, 16, v220
	v_and_b32_e32 v131, 0xffff0000, v220
	v_lshlrev_b32_e32 v134, 16, v221
	v_and_b32_e32 v135, 0xffff0000, v221
	v_lshlrev_b32_e32 v138, 16, v222
	v_and_b32_e32 v139, 0xffff0000, v222
	v_lshlrev_b32_e32 v140, 16, v223
	v_and_b32_e32 v141, 0xffff0000, v223
	s_waitcnt vmcnt(5)
	v_lshlrev_b32_e32 v142, 16, v224
	v_and_b32_e32 v143, 0xffff0000, v224
	v_lshlrev_b32_e32 v144, 16, v225
	v_and_b32_e32 v145, 0xffff0000, v225
	v_lshlrev_b32_e32 v146, 16, v226
	v_and_b32_e32 v147, 0xffff0000, v226
	v_lshlrev_b32_e32 v148, 16, v227
	v_and_b32_e32 v149, 0xffff0000, v227
	s_waitcnt vmcnt(4)
	v_lshlrev_b32_e32 v150, 16, v228
	v_and_b32_e32 v151, 0xffff0000, v228
	v_lshlrev_b32_e32 v152, 16, v229
	v_and_b32_e32 v153, 0xffff0000, v229
	v_lshlrev_b32_e32 v154, 16, v230
	v_and_b32_e32 v155, 0xffff0000, v230
	v_lshlrev_b32_e32 v156, 16, v231
	v_and_b32_e32 v157, 0xffff0000, v231
	s_waitcnt vmcnt(3)
	v_lshlrev_b32_e32 v126, 16, v232
	v_and_b32_e32 v127, 0xffff0000, v232
	v_lshlrev_b32_e32 v128, 16, v233
	v_and_b32_e32 v129, 0xffff0000, v233
	v_lshlrev_b32_e32 v132, 16, v234
	v_and_b32_e32 v133, 0xffff0000, v234
	v_lshlrev_b32_e32 v136, 16, v235
	v_and_b32_e32 v137, 0xffff0000, v235
	s_waitcnt vmcnt(2)
	v_lshlrev_b32_e32 v112, 16, v236
	v_and_b32_e32 v113, 0xffff0000, v236
	v_lshlrev_b32_e32 v114, 16, v237
	v_and_b32_e32 v115, 0xffff0000, v237
	v_lshlrev_b32_e32 v116, 16, v238
	v_and_b32_e32 v117, 0xffff0000, v238
	v_lshlrev_b32_e32 v120, 16, v239
	v_and_b32_e32 v121, 0xffff0000, v239
	s_waitcnt vmcnt(1)
	v_lshlrev_b32_e32 v50, 16, v240
	v_and_b32_e32 v51, 0xffff0000, v240
	v_lshlrev_b32_e32 v52, 16, v241
	v_and_b32_e32 v53, 0xffff0000, v241
	v_lshlrev_b32_e32 v56, 16, v242
	v_and_b32_e32 v57, 0xffff0000, v242
	v_lshlrev_b32_e32 v58, 16, v243
	v_and_b32_e32 v59, 0xffff0000, v243
	s_waitcnt vmcnt(0)
	v_lshlrev_b32_e32 v36, 16, v244
	v_and_b32_e32 v37, 0xffff0000, v244
	v_lshlrev_b32_e32 v38, 16, v245
	v_and_b32_e32 v39, 0xffff0000, v245
	v_lshlrev_b32_e32 v40, 16, v246
	v_and_b32_e32 v41, 0xffff0000, v246
	v_lshlrev_b32_e32 v42, 16, v247
	v_and_b32_e32 v43, 0xffff0000, v247
	s_waitcnt vmcnt(6)
	v_pk_fma_f32 v[44:45], v[20:21], v[150:151], 0 op_sel_hi:[1,1,0]
	v_pk_fma_f32 v[160:161], v[20:21], v[126:127], 0 op_sel_hi:[1,1,0]
	v_pk_fma_f32 v[46:47], v[22:23], v[152:153], 0 op_sel_hi:[1,1,0]
	v_pk_fma_f32 v[48:49], v[8:9], v[154:155], 0 op_sel_hi:[1,1,0]
	v_pk_fma_f32 v[162:163], v[22:23], v[128:129], 0 op_sel_hi:[1,1,0]
	v_pk_fma_f32 v[164:165], v[8:9], v[132:133], 0 op_sel_hi:[1,1,0]
	s_waitcnt vmcnt(5)
	v_pk_fma_f32 v[44:45], v[16:17], v[126:127], v[44:45]
	v_pk_fma_f32 v[160:161], v[16:17], v[112:113], v[160:161]
	v_pk_fma_f32 v[54:55], v[10:11], v[156:157], 0 op_sel_hi:[1,1,0]
	v_pk_fma_f32 v[166:167], v[10:11], v[136:137], 0 op_sel_hi:[1,1,0]
	v_pk_fma_f32 v[46:47], v[18:19], v[128:129], v[46:47]
	s_waitcnt vmcnt(4)
	v_pk_fma_f32 v[48:49], v[12:13], v[132:133], v[48:49]
	v_pk_fma_f32 v[162:163], v[18:19], v[114:115], v[162:163]
	v_pk_fma_f32 v[164:165], v[12:13], v[116:117], v[164:165]
	s_waitcnt vmcnt(3)
	v_pk_fma_f32 v[168:169], v[28:29], v[112:113], v[44:45]
	v_pk_fma_f32 v[44:45], v[28:29], v[50:51], v[160:161]
	v_pk_fma_f32 v[160:161], v[20:21], v[142:143], 0 op_sel_hi:[1,1,0]
	v_pk_fma_f32 v[54:55], v[14:15], v[136:137], v[54:55]
	v_pk_fma_f32 v[166:167], v[14:15], v[120:121], v[166:167]
	v_pk_fma_f32 v[170:171], v[30:31], v[114:115], v[46:47]
	s_waitcnt vmcnt(2)
	v_pk_fma_f32 v[174:175], v[24:25], v[116:117], v[48:49]
	v_pk_fma_f32 v[46:47], v[30:31], v[52:53], v[162:163]
	v_pk_fma_f32 v[48:49], v[24:25], v[56:57], v[164:165]
	v_pk_fma_f32 v[162:163], v[22:23], v[144:145], 0 op_sel_hi:[1,1,0]
	v_pk_fma_f32 v[164:165], v[8:9], v[146:147], 0 op_sel_hi:[1,1,0]
	v_pk_fma_f32 v[160:161], v[16:17], v[150:151], v[160:161]
	v_pk_fma_f32 v[176:177], v[26:27], v[120:121], v[54:55]
	v_pk_fma_f32 v[54:55], v[26:27], v[58:59], v[166:167]
	v_pk_fma_f32 v[166:167], v[10:11], v[148:149], 0 op_sel_hi:[1,1,0]
	v_pk_fma_f32 v[162:163], v[18:19], v[152:153], v[162:163]
	v_pk_fma_f32 v[164:165], v[12:13], v[154:155], v[164:165]
	v_pk_fma_f32 v[160:161], v[28:29], v[126:127], v[160:161]
	v_pk_fma_f32 v[166:167], v[14:15], v[156:157], v[166:167]
	v_pk_fma_f32 v[162:163], v[30:31], v[128:129], v[162:163]
	v_pk_fma_f32 v[164:165], v[24:25], v[132:133], v[164:165]
	s_waitcnt vmcnt(1)
; __device__ __forceinline__ float silu_f(float x) { return x * __builtin_amdgcn_rcpf(1.f + __builtin_amdgcn_exp2f(-1.4426950408889634f * x)); }
; __device__ __forceinline__ void prep_seg(const bf16_t* QK, const float* cw, const size_t rowbase, const int t0, const int h, const int seg, const int lane, float (&o)[8][8]) {
;     ...
; #pragma unroll
;         for (int j = 0; j < 4; ++j) { const int r = rr - j;
;             if (r >= 0 && r < 8) {
; #pragma unroll
;                 for (int e = 0; e < 8; ++e) o[r][e] += wt[j][e] * x[e]; } } }
; #pragma unroll
;     for (int r = 0; r < 8; ++r) { float ss = 0.f;
; #pragma unroll
;         for (int e = 0; e < 8; ++e) { o[r][e] = silu_f(o[r][e]); ss += o[r][e] * o[r][e]; }
	v_pk_fma_f32 v[112:113], v[0:1], v[112:113], v[160:161]
	v_pk_fma_f32 v[160:161], v[20:21], v[130:131], 0 op_sel_hi:[1,1,0]
	v_pk_fma_f32 v[166:167], v[26:27], v[136:137], v[166:167]
	v_pk_fma_f32 v[114:115], v[2:3], v[114:115], v[162:163]
	s_waitcnt vmcnt(0)
	v_pk_fma_f32 v[116:117], v[4:5], v[116:117], v[164:165]
	v_pk_fma_f32 v[162:163], v[22:23], v[134:135], 0 op_sel_hi:[1,1,0]
	v_pk_fma_f32 v[164:165], v[8:9], v[138:139], 0 op_sel_hi:[1,1,0]
	v_pk_fma_f32 v[160:161], v[16:17], v[142:143], v[160:161]
	v_pk_fma_f32 v[120:121], v[6:7], v[120:121], v[166:167]
	v_pk_fma_f32 v[166:167], v[10:11], v[140:141], 0 op_sel_hi:[1,1,0]
	v_pk_fma_f32 v[162:163], v[18:19], v[144:145], v[162:163]
	v_pk_fma_f32 v[164:165], v[12:13], v[146:147], v[164:165]
	v_pk_fma_f32 v[160:161], v[28:29], v[150:151], v[160:161]
	v_pk_fma_f32 v[166:167], v[14:15], v[148:149], v[166:167]
	v_pk_fma_f32 v[162:163], v[30:31], v[152:153], v[162:163]
	v_pk_fma_f32 v[164:165], v[24:25], v[154:155], v[164:165]
	v_pk_fma_f32 v[126:127], v[0:1], v[126:127], v[160:161]
	v_pk_fma_f32 v[160:161], v[20:21], v[102:103], 0 op_sel_hi:[1,1,0]
	v_pk_fma_f32 v[166:167], v[26:27], v[156:157], v[166:167]
	v_pk_fma_f32 v[128:129], v[2:3], v[128:129], v[162:163]
	v_pk_fma_f32 v[132:133], v[4:5], v[132:133], v[164:165]
	v_pk_fma_f32 v[162:163], v[22:23], v[122:123], 0 op_sel_hi:[1,1,0]
	v_pk_fma_f32 v[164:165], v[8:9], v[124:125], 0 op_sel_hi:[1,1,0]
	v_pk_fma_f32 v[160:161], v[16:17], v[130:131], v[160:161]
	v_pk_fma_f32 v[136:137], v[6:7], v[136:137], v[166:167]
	v_pk_fma_f32 v[166:167], v[10:11], v[118:119], 0 op_sel_hi:[1,1,0]
	v_pk_fma_f32 v[162:163], v[18:19], v[134:135], v[162:163]
	v_pk_fma_f32 v[164:165], v[12:13], v[138:139], v[164:165]
	v_pk_fma_f32 v[160:161], v[28:29], v[142:143], v[160:161]
	v_pk_fma_f32 v[166:167], v[14:15], v[140:141], v[166:167]
	v_pk_fma_f32 v[162:163], v[30:31], v[144:145], v[162:163]
	v_pk_fma_f32 v[164:165], v[24:25], v[146:147], v[164:165]
	v_pk_fma_f32 v[150:151], v[0:1], v[150:151], v[160:161]
	v_pk_fma_f32 v[160:161], v[20:21], v[104:105], 0 op_sel_hi:[1,1,0]
	v_pk_fma_f32 v[166:167], v[26:27], v[148:149], v[166:167]
	v_pk_fma_f32 v[152:153], v[2:3], v[152:153], v[162:163]
	v_pk_fma_f32 v[154:155], v[4:5], v[154:155], v[164:165]
	v_pk_fma_f32 v[162:163], v[22:23], v[106:107], 0 op_sel_hi:[1,1,0]
	v_pk_fma_f32 v[164:165], v[8:9], v[108:109], 0 op_sel_hi:[1,1,0]
	v_pk_fma_f32 v[160:161], v[16:17], v[102:103], v[160:161]
	v_pk_fma_f32 v[156:157], v[6:7], v[156:157], v[166:167]
	v_pk_fma_f32 v[166:167], v[10:11], v[110:111], 0 op_sel_hi:[1,1,0]
	v_pk_fma_f32 v[162:163], v[18:19], v[122:123], v[162:163]
	v_pk_fma_f32 v[164:165], v[12:13], v[124:125], v[164:165]
	v_pk_fma_f32 v[160:161], v[28:29], v[130:131], v[160:161]
	v_pk_fma_f32 v[166:167], v[14:15], v[118:119], v[166:167]
	v_pk_fma_f32 v[162:163], v[30:31], v[134:135], v[162:163]
	v_pk_fma_f32 v[164:165], v[24:25], v[138:139], v[164:165]
	v_pk_fma_f32 v[142:143], v[0:1], v[142:143], v[160:161]
	v_pk_fma_f32 v[160:161], v[20:21], v[60:61], 0 op_sel_hi:[1,1,0]
	v_pk_fma_f32 v[20:21], v[20:21], v[62:63], 0 op_sel_hi:[1,1,0]
	v_pk_fma_f32 v[166:167], v[26:27], v[140:141], v[166:167]
	v_pk_fma_f32 v[144:145], v[2:3], v[144:145], v[162:163]
	v_pk_fma_f32 v[146:147], v[4:5], v[146:147], v[164:165]
	v_pk_fma_f32 v[162:163], v[22:23], v[96:97], 0 op_sel_hi:[1,1,0]
	v_pk_fma_f32 v[164:165], v[8:9], v[98:99], 0 op_sel_hi:[1,1,0]
	v_pk_fma_f32 v[160:161], v[16:17], v[104:105], v[160:161]
	v_pk_fma_f32 v[22:23], v[22:23], v[90:91], 0 op_sel_hi:[1,1,0]
	v_pk_fma_f32 v[8:9], v[8:9], v[92:93], 0 op_sel_hi:[1,1,0]
	v_pk_fma_f32 v[16:17], v[16:17], v[60:61], v[20:21]
	v_pk_fma_f32 v[148:149], v[6:7], v[148:149], v[166:167]
	v_pk_fma_f32 v[166:167], v[10:11], v[100:101], 0 op_sel_hi:[1,1,0]
	v_pk_fma_f32 v[162:163], v[18:19], v[106:107], v[162:163]
	v_pk_fma_f32 v[164:165], v[12:13], v[108:109], v[164:165]
	v_pk_fma_f32 v[10:11], v[10:11], v[94:95], 0 op_sel_hi:[1,1,0]
	v_pk_fma_f32 v[18:19], v[18:19], v[96:97], v[22:23]
	v_pk_fma_f32 v[8:9], v[12:13], v[98:99], v[8:9]
	v_pk_fma_f32 v[12:13], v[28:29], v[104:105], v[16:17]
	v_pk_fma_f32 v[166:167], v[14:15], v[110:111], v[166:167]
	v_pk_fma_f32 v[10:11], v[14:15], v[100:101], v[10:11]
	v_pk_fma_f32 v[14:15], v[30:31], v[106:107], v[18:19]
	v_pk_fma_f32 v[8:9], v[24:25], v[108:109], v[8:9]
	v_pk_fma_f32 v[16:17], v[0:1], v[102:103], v[12:13]
	v_pk_fma_f32 v[12:13], v[2:3], v[122:123], v[14:15]
	v_pk_fma_f32 v[14:15], v[4:5], v[124:125], v[8:9]
	v_mul_f32_e32 v8, 0xbfb8aa3b, v16
	v_exp_f32_e32 v18, v8
	v_mul_f32_e32 v8, 0xbfb8aa3b, v17
	v_exp_f32_e32 v19, v8
	v_pk_fma_f32 v[10:11], v[26:27], v[110:111], v[10:11]
	v_pk_fma_f32 v[160:161], v[28:29], v[102:103], v[160:161]
	v_pk_fma_f32 v[8:9], v[6:7], v[118:119], v[10:11]
	v_add_f32_e32 v10, 1.0, v18
	v_mul_f32_e32 v11, 0xbfb8aa3b, v12
	v_rcp_f32_e32 v18, v10
	v_add_f32_e32 v10, 1.0, v19
	v_exp_f32_e32 v11, v11
	v_mul_f32_e32 v19, 0xbfb8aa3b, v13
	v_exp_f32_e32 v21, v19
	v_rcp_f32_e32 v19, v10
	v_add_f32_e32 v10, 1.0, v11
	v_rcp_f32_e32 v20, v10
	v_add_f32_e32 v10, 1.0, v21
	v_mul_f32_e32 v11, 0xbfb8aa3b, v14
	v_mul_f32_e32 v21, 0xbfb8aa3b, v15
	v_exp_f32_e32 v11, v11
	v_exp_f32_e32 v22, v21
	v_rcp_f32_e32 v21, v10
	v_pk_fma_f32 v[130:131], v[0:1], v[130:131], v[160:161]
	v_add_f32_e32 v10, 1.0, v11
	v_add_f32_e32 v11, 1.0, v22
	v_rcp_f32_e32 v10, v10
	v_rcp_f32_e32 v11, v11
	v_pk_fma_f32 v[162:163], v[30:31], v[122:123], v[162:163]
	v_pk_fma_f32 v[164:165], v[24:25], v[124:125], v[164:165]
	v_pk_fma_f32 v[134:135], v[2:3], v[134:135], v[162:163]
	v_pk_mul_f32 v[10:11], v[14:15], v[10:11]
	v_pk_mul_f32 v[14:15], v[16:17], v[18:19]
; __device__ __forceinline__ float silu_f(float x) { return x * __builtin_amdgcn_rcpf(1.f + __builtin_amdgcn_exp2f(-1.4426950408889634f * x)); }
; __device__ __forceinline__ void prep_seg(const bf16_t* QK, const float* cw, const size_t rowbase, const int t0, const int h, const int seg, const int lane, float (&o)[8][8]) {
;     ...
;     for (int r = 0; r < 8; ++r) { float ss = 0.f;
; #pragma unroll
;         for (int e = 0; e < 8; ++e) { o[r][e] = silu_f(o[r][e]); ss += o[r][e] * o[r][e]; }
;         if (seg < 2) { ss += __shfl_xor(ss, 1); ss += __shfl_xor(ss, 2); ss += __shfl_xor(ss, 4); const float sc = rsqrtf(ss + 1e-6f) * (seg == 0 ? 0.125f : 1.f);
; #pragma unroll
;             for (int e = 0; e < 8; ++e) o[r][e] *= sc; } }
	v_mul_f32_e32 v16, 0xbfb8aa3b, v130
	v_exp_f32_e32 v18, v16
	v_mul_f32_e32 v16, 0xbfb8aa3b, v131
	v_exp_f32_e32 v19, v16
	v_pk_fma_f32 v[138:139], v[4:5], v[138:139], v[164:165]
	v_add_f32_e32 v18, 1.0, v18
	v_rcp_f32_e32 v28, v18
	v_add_f32_e32 v18, 1.0, v19
	v_rcp_f32_e32 v29, v18
	v_mul_f32_e32 v18, 0xbfb8aa3b, v134
	v_pk_mul_f32 v[12:13], v[12:13], v[20:21]
	v_exp_f32_e32 v18, v18
	v_mul_f32_e32 v20, 0xbfb8aa3b, v138
	v_exp_f32_e32 v21, v20
	v_pk_fma_f32 v[166:167], v[26:27], v[118:119], v[166:167]
	v_mul_f32_e32 v19, 0xbfb8aa3b, v135
	v_pk_fma_f32 v[140:141], v[6:7], v[140:141], v[166:167]
	v_exp_f32_e32 v19, v19
	v_add_f32_e32 v18, 1.0, v18
	v_rcp_f32_e32 v20, v18
	v_add_f32_e32 v18, 1.0, v21
	v_mul_f32_e32 v21, 0xbfb8aa3b, v140
	v_exp_f32_e32 v21, v21
	v_mul_f32_e32 v30, 0xbfb8aa3b, v141
	v_exp_f32_e32 v31, v30
	v_add_f32_e32 v60, 1.0, v19
	v_mul_f32_e32 v19, 0xbfb8aa3b, v139
	v_exp_f32_e32 v19, v19
	v_mul_f32_e32 v22, 0xbfb8aa3b, v8
	v_mul_f32_e32 v23, 0xbfb8aa3b, v9
	v_add_f32_e32 v21, 1.0, v21
	v_exp_f32_e32 v22, v22
	v_exp_f32_e32 v23, v23
	v_rcp_f32_e32 v30, v21
	v_add_f32_e32 v21, 1.0, v31
	v_rcp_f32_e32 v31, v21
	v_rcp_f32_e32 v21, v60
	v_add_f32_e32 v19, 1.0, v19
	v_rcp_f32_e32 v18, v18
	v_rcp_f32_e32 v19, v19
	v_add_f32_e32 v22, 1.0, v22
	v_add_f32_e32 v23, 1.0, v23
	v_pk_mul_f32 v[62:63], v[130:131], v[28:29]
	v_rcp_f32_e32 v22, v22
	v_rcp_f32_e32 v23, v23
	v_xor_b32_e32 v24, 1, v202
	v_add_u32_e32 v64, 64, v203
	v_pk_mul_f32 v[16:17], v[14:15], v[14:15]
	v_pk_mul_f32 v[20:21], v[134:135], v[20:21]
	v_pk_mul_f32 v[28:29], v[62:63], v[62:63]
	v_cmp_lt_i32_e32 vcc, v24, v64
	v_pk_mul_f32 v[26:27], v[12:13], v[12:13]
	v_pk_mul_f32 v[92:93], v[20:21], v[20:21]
	v_mov_b32_e32 v94, v28
	v_mov_b32_e32 v95, v16
	v_mov_b32_e32 v16, v29
	v_cndmask_b32_e32 v24, v202, v24, vcc
	v_pk_mul_f32 v[18:19], v[138:139], v[18:19]
	v_pk_add_f32 v[16:17], v[94:95], v[16:17]
	v_mov_b32_e32 v28, v92
	v_mov_b32_e32 v29, v26
	v_pk_fma_f32 v[56:57], v[4:5], v[56:57], v[174:175]
	v_lshlrev_b32_e32 v174, 2, v24
	v_pk_mul_f32 v[24:25], v[10:11], v[10:11]
	v_pk_mul_f32 v[90:91], v[18:19], v[18:19]
	v_pk_add_f32 v[16:17], v[28:29], v[16:17]
	v_mov_b32_e32 v26, v93
	v_pk_mul_f32 v[8:9], v[8:9], v[22:23]
	v_pk_mul_f32 v[60:61], v[140:141], v[30:31]
	v_pk_add_f32 v[16:17], v[26:27], v[16:17]
	v_mov_b32_e32 v26, v90
	v_mov_b32_e32 v27, v24
	v_pk_mul_f32 v[22:23], v[8:9], v[8:9]
	v_pk_mul_f32 v[30:31], v[60:61], v[60:61]
	v_pk_add_f32 v[16:17], v[26:27], v[16:17]
	v_mov_b32_e32 v24, v91
	v_pk_add_f32 v[16:17], v[24:25], v[16:17]
	v_mov_b32_e32 v24, v30
	v_mov_b32_e32 v25, v22
	v_pk_add_f32 v[16:17], v[24:25], v[16:17]
	v_mov_b32_e32 v22, v31
	v_pk_add_f32 v[16:17], v[22:23], v[16:17]
	ds_bpermute_b32 v23, v174, v17
	ds_bpermute_b32 v22, v174, v16
	v_xor_b32_e32 v24, 2, v202
	v_cmp_lt_i32_e32 vcc, v24, v64
	v_pk_fma_f32 v[58:59], v[6:7], v[58:59], v[176:177]
	v_mul_f32_e32 v71, 0xbfb8aa3b, v154
	v_cndmask_b32_e32 v24, v202, v24, vcc
	v_lshlrev_b32_e32 v175, 2, v24
	s_waitcnt lgkmcnt(0)
	v_pk_add_f32 v[16:17], v[16:17], v[22:23]
	ds_bpermute_b32 v23, v175, v17
	ds_bpermute_b32 v22, v175, v16
	v_xor_b32_e32 v24, 4, v202
	v_cmp_lt_i32_e32 vcc, v24, v64
	v_exp_f32_e32 v71, v71
	v_mul_f32_e32 v25, 0xbfb8aa3b, v145
	v_cndmask_b32_e32 v24, v202, v24, vcc
	v_lshlrev_b32_e32 v176, 2, v24
	s_waitcnt lgkmcnt(0)
	v_pk_add_f32 v[16:17], v[16:17], v[22:23]
	ds_bpermute_b32 v23, v176, v17
	ds_bpermute_b32 v22, v176, v16
	v_mul_f32_e32 v24, 0xbfb8aa3b, v144
	v_exp_f32_e32 v24, v24
	v_exp_f32_e32 v25, v25
	v_mul_f32_e32 v26, 0xbfb8aa3b, v146
	s_waitcnt lgkmcnt(0)
	v_pk_add_f32 v[16:17], v[16:17], v[22:23]
	v_mul_f32_e32 v23, 0xbfb8aa3b, v143
	v_pk_add_f32 v[16:17], v[16:17], s[68:69] op_sel_hi:[1,0]
	v_exp_f32_e32 v23, v23
	v_mul_f32_e32 v22, 0x4b800000, v17
	v_cmp_gt_f32_e32 vcc, s73, v17
	v_mul_f32_e32 v27, 0xbfb8aa3b, v147
	v_add_f32_e32 v23, 1.0, v23
	v_cndmask_b32_e32 v17, v17, v22, vcc
	v_mul_f32_e32 v22, 0xbfb8aa3b, v142
	v_exp_f32_e32 v22, v22
	v_rcp_f32_e32 v23, v23
	v_exp_f32_e32 v26, v26
	v_exp_f32_e32 v27, v27
	v_add_f32_e32 v22, 1.0, v22
	v_rcp_f32_e32 v22, v22
	v_mul_f32_e32 v28, 0xbfb8aa3b, v148
	v_mul_f32_e32 v29, 0xbfb8aa3b, v149
	v_mul_f32_e32 v73, 0xbfb8aa3b, v157
	v_pk_mul_f32 v[94:95], v[142:143], v[22:23]
	v_mul_f32_e32 v22, 0xbfb8aa3b, v150
	v_exp_f32_e32 v67, v22
	v_mul_f32_e32 v22, 0xbfb8aa3b, v151
	v_exp_f32_e32 v69, v22
	v_add_f32_e32 v24, 1.0, v24
	v_add_f32_e32 v67, 1.0, v67
	v_rcp_f32_e32 v96, v67
	v_add_f32_e32 v67, 1.0, v69
	v_rcp_f32_e32 v97, v67
	v_mul_f32_e32 v67, 0xbfb8aa3b, v152
	v_exp_f32_e32 v67, v67
	v_mul_f32_e32 v69, 0xbfb8aa3b, v153
	v_exp_f32_e32 v69, v69
	v_add_f32_e32 v25, 1.0, v25
	v_add_f32_e32 v67, 1.0, v67
	v_rcp_f32_e32 v98, v67
	v_add_f32_e32 v67, 1.0, v69
	v_add_f32_e32 v69, 1.0, v71
	v_rcp_f32_e32 v100, v69
	v_mul_f32_e32 v69, 0xbfb8aa3b, v155
	v_mul_f32_e32 v71, 0xbfb8aa3b, v156
	v_exp_f32_e32 v69, v69
	v_exp_f32_e32 v71, v71
	v_exp_f32_e32 v28, v28
	v_exp_f32_e32 v29, v29
	v_exp_f32_e32 v73, v73
	v_rcp_f32_e32 v24, v24
	v_rcp_f32_e32 v25, v25
	v_rcp_f32_e32 v99, v67
	v_add_f32_e32 v26, 1.0, v26
	v_add_f32_e32 v27, 1.0, v27
	v_add_f32_e32 v69, 1.0, v69
	v_rcp_f32_e32 v26, v26
	v_rcp_f32_e32 v27, v27
	v_add_f32_e32 v71, 1.0, v71
	v_rcp_f32_e32 v101, v69
	v_add_f32_e32 v28, 1.0, v28
	v_add_f32_e32 v29, 1.0, v29
	v_rcp_f32_e32 v102, v71
	v_add_f32_e32 v71, 1.0, v73
	v_pk_mul_f32 v[124:125], v[150:151], v[96:97]
	v_rcp_f32_e32 v28, v28
	v_rcp_f32_e32 v29, v29
	v_pk_mul_f32 v[92:93], v[144:145], v[24:25]
	v_pk_mul_f32 v[22:23], v[94:95], v[94:95]
	v_rcp_f32_e32 v103, v71
	v_pk_mul_f32 v[122:123], v[152:153], v[98:99]
	v_pk_mul_f32 v[96:97], v[124:125], v[124:125]
	v_pk_mul_f32 v[24:25], v[92:93], v[92:93]
	v_pk_mul_f32 v[98:99], v[122:123], v[122:123]
	v_mov_b32_e32 v104, v96
	v_mov_b32_e32 v105, v22
	v_mov_b32_e32 v22, v97
	v_pk_mul_f32 v[30:31], v[146:147], v[26:27]
	v_pk_mul_f32 v[118:119], v[154:155], v[100:101]
	v_pk_add_f32 v[22:23], v[104:105], v[22:23]
	v_mov_b32_e32 v96, v98
	v_mov_b32_e32 v97, v24
	v_pk_mul_f32 v[26:27], v[30:31], v[30:31]
	v_pk_mul_f32 v[100:101], v[118:119], v[118:119]
	v_pk_add_f32 v[22:23], v[96:97], v[22:23]
	v_mov_b32_e32 v24, v99
	v_pk_mul_f32 v[28:29], v[148:149], v[28:29]
	v_pk_mul_f32 v[110:111], v[156:157], v[102:103]
	v_pk_add_f32 v[22:23], v[24:25], v[22:23]
	v_mov_b32_e32 v24, v100
	v_mov_b32_e32 v25, v26
	v_pk_mul_f32 v[90:91], v[28:29], v[28:29]
	v_pk_mul_f32 v[102:103], v[110:111], v[110:111]
	v_pk_add_f32 v[22:23], v[24:25], v[22:23]
	v_mov_b32_e32 v26, v101
	v_pk_add_f32 v[22:23], v[26:27], v[22:23]
	v_mov_b32_e32 v24, v102
	v_mov_b32_e32 v25, v90
	v_pk_add_f32 v[22:23], v[24:25], v[22:23]
	v_mov_b32_e32 v90, v103
	v_rsq_f32_e32 v17, v17
	v_pk_add_f32 v[90:91], v[90:91], v[22:23]
	ds_bpermute_b32 v97, v174, v91
	ds_bpermute_b32 v96, v174, v90
	v_mul_f32_e32 v64, 0x45800000, v17
	v_cndmask_b32_e32 v64, v17, v64, vcc
	v_pk_mul_f32 v[22:23], v[10:11], v[64:65] op_sel_hi:[1,0]
	v_pk_mul_f32 v[24:25], v[12:13], v[64:65] op_sel_hi:[1,0]
	s_waitcnt lgkmcnt(0)
; __device__ __forceinline__ float silu_f(float x) { return x * __builtin_amdgcn_rcpf(1.f + __builtin_amdgcn_exp2f(-1.4426950408889634f * x)); }
; __device__ __forceinline__ void prep_seg(const bf16_t* QK, const float* cw, const size_t rowbase, const int t0, const int h, const int seg, const int lane, float (&o)[8][8]) {
;     ...
;     for (int r = 0; r < 8; ++r) { float ss = 0.f;
; #pragma unroll
;         for (int e = 0; e < 8; ++e) { o[r][e] = silu_f(o[r][e]); ss += o[r][e] * o[r][e]; }
;         if (seg < 2) { ss += __shfl_xor(ss, 1); ss += __shfl_xor(ss, 2); ss += __shfl_xor(ss, 4); const float sc = rsqrtf(ss + 1e-6f) * (seg == 0 ? 0.125f : 1.f);
; #pragma unroll
;             for (int e = 0; e < 8; ++e) o[r][e] *= sc; } }
	v_pk_add_f32 v[10:11], v[90:91], v[96:97]
	ds_bpermute_b32 v13, v175, v11
	ds_bpermute_b32 v12, v175, v10
	v_pk_mul_f32 v[26:27], v[14:15], v[64:65] op_sel_hi:[1,0]
	v_mul_f32_e32 v14, 0x4b800000, v16
	v_cmp_gt_f32_e32 vcc, s73, v16
	v_mul_f32_e32 v67, 0xbfb8aa3b, v137
	s_waitcnt lgkmcnt(0)
	v_pk_add_f32 v[10:11], v[10:11], v[12:13]
	v_cndmask_b32_e32 v14, v16, v14, vcc
	v_rsq_f32_e32 v14, v14
	ds_bpermute_b32 v13, v176, v11
	ds_bpermute_b32 v12, v176, v10
	v_pk_mul_f32 v[16:17], v[8:9], v[64:65] op_sel_hi:[1,0]
	v_mul_f32_e32 v8, 0x45800000, v14
	v_cndmask_b32_e32 v8, v14, v8, vcc
	v_pk_mul_f32 v[14:15], v[62:63], v[8:9] op_sel_hi:[1,0]
	s_waitcnt lgkmcnt(0)
	v_pk_add_f32 v[10:11], v[10:11], v[12:13]
	v_mul_f32_e32 v12, 0xbfb8aa3b, v126
	v_pk_add_f32 v[62:63], v[10:11], s[68:69] op_sel_hi:[1,0]
	v_mul_f32_e32 v64, 0xbfb8aa3b, v132
	v_mul_f32_e32 v9, 0x4b800000, v63
	v_cmp_gt_f32_e32 vcc, s73, v63
	v_exp_f32_e32 v64, v64
	v_exp_f32_e32 v67, v67
	v_cndmask_b32_e32 v9, v63, v9, vcc
	v_rsq_f32_e32 v9, v9
	v_pk_fma_f32 v[50:51], v[0:1], v[50:51], v[168:169]
	v_pk_fma_f32 v[52:53], v[2:3], v[52:53], v[170:171]
	v_mul_f32_e32 v69, 0xbfb8aa3b, v51
	v_pk_mul_f32 v[20:21], v[20:21], v[8:9] op_sel_hi:[1,0]
	v_pk_mul_f32 v[18:19], v[18:19], v[8:9] op_sel_hi:[1,0]
	v_pk_mul_f32 v[10:11], v[60:61], v[8:9] op_sel_hi:[1,0]
	v_mul_f32_e32 v8, 0x45800000, v9
	v_cndmask_b32_e32 v60, v9, v8, vcc
	v_pk_mul_f32 v[8:9], v[94:95], v[60:61] op_sel_hi:[1,0]
	v_exp_f32_e32 v61, v12
	v_mul_f32_e32 v12, 0xbfb8aa3b, v127
	v_exp_f32_e32 v63, v12
	v_cmp_gt_f32_e32 vcc, s73, v62
	v_pk_mul_f32 v[12:13], v[92:93], v[60:61] op_sel_hi:[1,0]
	v_add_f32_e32 v61, 1.0, v61
	v_rcp_f32_e32 v90, v61
	v_add_f32_e32 v61, 1.0, v63
	v_rcp_f32_e32 v91, v61
	v_mul_f32_e32 v61, 0xbfb8aa3b, v128
	v_exp_f32_e32 v61, v61
	v_mul_f32_e32 v63, 0xbfb8aa3b, v129
	v_exp_f32_e32 v63, v63
	v_pk_mul_f32 v[100:101], v[126:127], v[90:91]
	v_add_f32_e32 v61, 1.0, v61
	v_rcp_f32_e32 v92, v61
	v_add_f32_e32 v61, 1.0, v63
	v_add_f32_e32 v63, 1.0, v64
	v_rcp_f32_e32 v96, v63
	v_mul_f32_e32 v63, 0xbfb8aa3b, v133
	v_exp_f32_e32 v63, v63
	v_rcp_f32_e32 v93, v61
	v_mul_f32_e32 v61, 0xbfb8aa3b, v112
	v_mul_f32_e32 v64, 0xbfb8aa3b, v136
	v_add_f32_e32 v63, 1.0, v63
	v_rcp_f32_e32 v97, v63
	v_exp_f32_e32 v61, v61
	v_mul_f32_e32 v63, 0xbfb8aa3b, v113
	v_exp_f32_e32 v64, v64
	v_exp_f32_e32 v63, v63
	v_add_f32_e32 v61, 1.0, v61
	v_rcp_f32_e32 v108, v61
	v_add_f32_e32 v64, 1.0, v64
	v_add_f32_e32 v61, 1.0, v63
	v_rcp_f32_e32 v94, v64
	v_add_f32_e32 v64, 1.0, v67
	v_rcp_f32_e32 v109, v61
	v_mul_f32_e32 v61, 0xbfb8aa3b, v114
	v_rcp_f32_e32 v95, v64
	v_exp_f32_e32 v61, v61
	v_mul_f32_e32 v63, 0xbfb8aa3b, v115
	v_mul_f32_e32 v64, 0xbfb8aa3b, v116
	v_exp_f32_e32 v63, v63
	v_exp_f32_e32 v64, v64
	v_add_f32_e32 v61, 1.0, v61
	v_rcp_f32_e32 v106, v61
	v_add_f32_e32 v61, 1.0, v63
	v_add_f32_e32 v63, 1.0, v64
	v_rcp_f32_e32 v104, v63
	v_mul_f32_e32 v63, 0xbfb8aa3b, v117
	v_mul_f32_e32 v64, 0xbfb8aa3b, v120
	v_exp_f32_e32 v63, v63
	v_exp_f32_e32 v64, v64
	v_mul_f32_e32 v67, 0xbfb8aa3b, v121
	v_exp_f32_e32 v67, v67
	v_rcp_f32_e32 v107, v61
	v_add_f32_e32 v63, 1.0, v63
	v_add_f32_e32 v64, 1.0, v64
	v_rcp_f32_e32 v105, v63
	v_rcp_f32_e32 v102, v64
	v_add_f32_e32 v64, 1.0, v67
	v_pk_mul_f32 v[108:109], v[112:113], v[108:109]
	v_pk_mul_f32 v[98:99], v[128:129], v[92:93]
	v_pk_mul_f32 v[90:91], v[100:101], v[100:101]
	v_rcp_f32_e32 v103, v64
	v_pk_mul_f32 v[106:107], v[114:115], v[106:107]
	v_pk_mul_f32 v[112:113], v[108:109], v[108:109]
	v_pk_mul_f32 v[92:93], v[98:99], v[98:99]
	v_pk_mul_f32 v[114:115], v[106:107], v[106:107]
	v_mov_b32_e32 v126, v112
	v_mov_b32_e32 v127, v90
	v_mov_b32_e32 v90, v113
	v_pk_mul_f32 v[96:97], v[132:133], v[96:97]
	v_pk_mul_f32 v[104:105], v[116:117], v[104:105]
	v_pk_add_f32 v[90:91], v[126:127], v[90:91]
	v_mov_b32_e32 v112, v114
	v_mov_b32_e32 v113, v92
	v_pk_mul_f32 v[132:133], v[96:97], v[96:97]
	v_pk_mul_f32 v[116:117], v[104:105], v[104:105]
	v_pk_add_f32 v[90:91], v[112:113], v[90:91]
	v_mov_b32_e32 v92, v115
	v_pk_mul_f32 v[94:95], v[136:137], v[94:95]
	v_pk_mul_f32 v[102:103], v[120:121], v[102:103]
	v_pk_add_f32 v[90:91], v[92:93], v[90:91]
	v_mov_b32_e32 v92, v116
	v_mov_b32_e32 v93, v132
	v_pk_mul_f32 v[130:131], v[94:95], v[94:95]
	v_pk_mul_f32 v[120:121], v[102:103], v[102:103]
	v_pk_add_f32 v[90:91], v[92:93], v[90:91]
	v_mov_b32_e32 v132, v117
	v_pk_add_f32 v[90:91], v[132:133], v[90:91]
	v_mov_b32_e32 v92, v120
	v_mov_b32_e32 v93, v130
	v_pk_add_f32 v[90:91], v[92:93], v[90:91]
	v_mov_b32_e32 v130, v121
	v_pk_add_f32 v[90:91], v[130:131], v[90:91]
	ds_bpermute_b32 v93, v174, v91
	ds_bpermute_b32 v92, v174, v90
	v_mul_f32_e32 v61, 0x4b800000, v62
	v_cndmask_b32_e32 v61, v62, v61, vcc
	v_rsq_f32_e32 v61, v61
	v_mul_f32_e32 v67, 0xbfb8aa3b, v50
	s_waitcnt lgkmcnt(0)
	v_pk_add_f32 v[62:63], v[90:91], v[92:93]
	ds_bpermute_b32 v113, v175, v63
	ds_bpermute_b32 v112, v175, v62
	v_exp_f32_e32 v67, v67
	v_exp_f32_e32 v69, v69
	v_pk_mul_f32 v[90:91], v[28:29], v[60:61] op_sel_hi:[1,0]
	v_mul_f32_e32 v28, 0x45800000, v61
	s_waitcnt lgkmcnt(0)
	v_pk_add_f32 v[112:113], v[62:63], v[112:113]
	ds_bpermute_b32 v115, v176, v113
	ds_bpermute_b32 v114, v176, v112
	v_cndmask_b32_e32 v28, v61, v28, vcc
	v_add_f32_e32 v67, 1.0, v67
	v_pk_mul_f32 v[92:93], v[30:31], v[60:61] op_sel_hi:[1,0]
	v_pk_mul_f32 v[62:63], v[124:125], v[28:29] op_sel_hi:[1,0]
	v_pk_mul_f32 v[60:61], v[122:123], v[28:29] op_sel_hi:[1,0]
	v_pk_mul_f32 v[30:31], v[118:119], v[28:29] op_sel_hi:[1,0]
	v_pk_mul_f32 v[28:29], v[110:111], v[28:29] op_sel_hi:[1,0]
	s_waitcnt lgkmcnt(0)
; __device__ __forceinline__ float silu_f(float x) { return x * __builtin_amdgcn_rcpf(1.f + __builtin_amdgcn_exp2f(-1.4426950408889634f * x)); }
; #define GAS __attribute__((address_space(1)))
; #define LAS __attribute__((address_space(3)))
; __device__ __forceinline__ v4u pk8(const float (&a)[8], const float s) { return (v4u){pk2(a[0] * s, a[1] * s), pk2(a[2] * s, a[3] * s), pk2(a[4] * s, a[5] * s), pk2(a[6] * s, a[7] * s)}; }
; __device__ __forceinline__ void prep_seg(const bf16_t* QK, const float* cw, const size_t rowbase, const int t0, const int h, const int seg, const int lane, float (&o)[8][8]) {
;     ...
;     for (int r = 0; r < 8; ++r) { float ss = 0.f;
; #pragma unroll
;         for (int e = 0; e < 8; ++e) { o[r][e] = silu_f(o[r][e]); ss += o[r][e] * o[r][e]; }
;         if (seg < 2) { ss += __shfl_xor(ss, 1); ss += __shfl_xor(ss, 2); ss += __shfl_xor(ss, 4); const float sc = rsqrtf(ss + 1e-6f) * (seg == 0 ? 0.125f : 1.f);
; #pragma unroll
;             for (int e = 0; e < 8; ++e) o[r][e] *= sc; } }
; __device__ __forceinline__ void intra_item(Frame& F, const int item, LAS unsigned char* SA, LAS unsigned char* SB, LAS float* GC, LAS float* BT) {
;     ...
;     prep_seg(QK, cw, rowbase, t0, h, 1, lane, o);
; #pragma unroll
;     for (int r = 0; r < 8; ++r) { const int c = 8 * rg + r; *(LAS v4u*)(SA + c * STRB + cg * 16) = pk8(o[r], 1.f); *(GAS v4u*)(gi + 3 * 8192 + c * 128 + cg * 16) = pk8(o[r], __expf(gl - GC[c])); }
	v_pk_add_f32 v[110:111], v[112:113], v[114:115]
	v_rcp_f32_e32 v112, v67
	v_add_f32_e32 v67, 1.0, v69
	v_rcp_f32_e32 v113, v67
	v_mul_f32_e32 v67, 0xbfb8aa3b, v52
	v_exp_f32_e32 v67, v67
	v_mul_f32_e32 v69, 0xbfb8aa3b, v53
	v_exp_f32_e32 v69, v69
	v_pk_fma_f32 v[6:7], v[6:7], v[42:43], v[54:55]
	v_add_f32_e32 v67, 1.0, v67
	v_mul_f32_e32 v42, 0xbfb8aa3b, v6
	v_rcp_f32_e32 v114, v67
	v_add_f32_e32 v67, 1.0, v69
	v_exp_f32_e32 v54, v42
	v_mul_f32_e32 v42, 0xbfb8aa3b, v7
	v_rcp_f32_e32 v115, v67
	v_exp_f32_e32 v55, v42
	v_pk_fma_f32 v[4:5], v[4:5], v[40:41], v[48:49]
	v_mul_f32_e32 v73, 0xbfb8aa3b, v56
	v_pk_mul_f32 v[42:43], v[52:53], v[114:115]
	v_add_f32_e32 v52, 1.0, v54
	v_add_f32_e32 v53, 1.0, v55
	v_rcp_f32_e32 v52, v52
	v_rcp_f32_e32 v53, v53
	v_exp_f32_e32 v73, v73
	v_pk_fma_f32 v[2:3], v[2:3], v[38:39], v[46:47]
	v_pk_fma_f32 v[0:1], v[0:1], v[36:37], v[44:45]
	v_pk_mul_f32 v[114:115], v[6:7], v[52:53]
	v_mul_f32_e32 v6, 0xbfb8aa3b, v4
	v_exp_f32_e32 v40, v6
	v_mul_f32_e32 v6, 0xbfb8aa3b, v5
	v_exp_f32_e32 v41, v6
	v_mul_f32_e32 v38, 0xbfb8aa3b, v2
	v_mul_f32_e32 v36, 0xbfb8aa3b, v0
	v_mul_f32_e32 v37, 0xbfb8aa3b, v1
	v_add_f32_e32 v40, 1.0, v40
	v_add_f32_e32 v41, 1.0, v41
	v_exp_f32_e32 v46, v38
	v_mul_f32_e32 v38, 0xbfb8aa3b, v3
	v_exp_f32_e32 v36, v36
	v_exp_f32_e32 v37, v37
	v_add_f32_e32 v69, 1.0, v73
	v_rcp_f32_e32 v40, v40
	v_rcp_f32_e32 v41, v41
	v_exp_f32_e32 v47, v38
	v_rcp_f32_e32 v116, v69
	v_mul_f32_e32 v69, 0xbfb8aa3b, v57
	v_mul_f32_e32 v73, 0xbfb8aa3b, v58
	v_exp_f32_e32 v69, v69
	v_exp_f32_e32 v73, v73
	v_mul_f32_e32 v75, 0xbfb8aa3b, v59
	v_add_f32_e32 v36, 1.0, v36
	v_add_f32_e32 v37, 1.0, v37
	v_exp_f32_e32 v75, v75
	v_pk_mul_f32 v[38:39], v[4:5], v[40:41]
	v_add_f32_e32 v4, 1.0, v46
	v_add_f32_e32 v5, 1.0, v47
	v_rcp_f32_e32 v36, v36
	v_rcp_f32_e32 v37, v37
	v_rcp_f32_e32 v4, v4
	v_rcp_f32_e32 v5, v5
	v_add_f32_e32 v69, 1.0, v69
	v_add_f32_e32 v73, 1.0, v73
	v_rcp_f32_e32 v117, v69
	v_rcp_f32_e32 v118, v73
	v_add_f32_e32 v73, 1.0, v75
	v_pk_mul_f32 v[50:51], v[50:51], v[112:113]
	v_pk_mul_f32 v[36:37], v[0:1], v[36:37]
	v_rcp_f32_e32 v119, v73
	v_pk_mul_f32 v[112:113], v[50:51], v[50:51]
	v_pk_mul_f32 v[44:45], v[2:3], v[4:5]
	v_pk_mul_f32 v[0:1], v[36:37], v[36:37]
	v_pk_mul_f32 v[54:55], v[42:43], v[42:43]
	v_pk_mul_f32 v[2:3], v[44:45], v[44:45]
	v_mov_b32_e32 v4, v0
	v_mov_b32_e32 v5, v112
	v_mov_b32_e32 v112, v1
	v_pk_mul_f32 v[56:57], v[56:57], v[116:117]
	v_pk_add_f32 v[0:1], v[4:5], v[112:113]
	v_mov_b32_e32 v4, v2
	v_mov_b32_e32 v5, v54
	v_pk_mul_f32 v[116:117], v[56:57], v[56:57]
	v_pk_mul_f32 v[40:41], v[38:39], v[38:39]
	v_pk_add_f32 v[0:1], v[4:5], v[0:1]
	v_mov_b32_e32 v54, v3
	v_pk_mul_f32 v[118:119], v[58:59], v[118:119]
	v_pk_add_f32 v[0:1], v[54:55], v[0:1]
	v_mov_b32_e32 v2, v40
	v_mov_b32_e32 v3, v116
	v_pk_mul_f32 v[58:59], v[118:119], v[118:119]
	v_pk_mul_f32 v[6:7], v[114:115], v[114:115]
	v_pk_add_f32 v[0:1], v[2:3], v[0:1]
	v_mov_b32_e32 v116, v41
	v_pk_add_f32 v[0:1], v[116:117], v[0:1]
	v_mov_b32_e32 v2, v6
	v_mov_b32_e32 v3, v58
	v_pk_add_f32 v[0:1], v[2:3], v[0:1]
	v_mov_b32_e32 v58, v7
	v_pk_add_f32 v[0:1], v[58:59], v[0:1]
	ds_bpermute_b32 v3, v174, v1
	ds_bpermute_b32 v2, v174, v0
	v_pk_add_f32 v[110:111], v[110:111], s[68:69] op_sel_hi:[1,0]
	v_mul_lo_u32 v40, v158, s74
	v_mul_f32_e32 v64, 0x4b800000, v111
	v_cmp_gt_f32_e32 vcc, s73, v111
	s_waitcnt lgkmcnt(0)
	v_pk_add_f32 v[0:1], v[0:1], v[2:3]
	ds_bpermute_b32 v3, v175, v1
	v_cndmask_b32_e32 v64, v111, v64, vcc
	v_rsq_f32_e32 v64, v64
	ds_bpermute_b32 v2, v175, v0
	v_lshl_add_u32 v177, v158, 2, s31
	s_mul_i32 s22, s80, 0xa000
	v_mul_f32_e32 v71, 0x45800000, v64
	v_cndmask_b32_e32 v4, v64, v71, vcc
	s_waitcnt lgkmcnt(0)
	v_pk_add_f32 v[0:1], v[0:1], v[2:3]
	v_pk_mul_f32 v[46:47], v[100:101], v[4:5] op_sel_hi:[1,0]
	v_pk_mul_f32 v[98:99], v[98:99], v[4:5] op_sel_hi:[1,0]
	v_pk_mul_f32 v[96:97], v[96:97], v[4:5] op_sel_hi:[1,0]
	v_mul_f32_e32 v5, 0x4b800000, v110
	v_cmp_gt_f32_e32 vcc, s73, v110
	ds_bpermute_b32 v3, v176, v1
	ds_bpermute_b32 v2, v176, v0
	v_cndmask_b32_e32 v5, v110, v5, vcc
	v_rsq_f32_e32 v5, v5
	s_mul_hi_i32 s23, s80, 0xa000
	s_add_u32 s22, s33, s22
	s_waitcnt lgkmcnt(0)
	v_pk_add_f32 v[0:1], v[0:1], v[2:3]
	v_pk_mul_f32 v[100:101], v[94:95], v[4:5] op_sel_hi:[1,0]
	v_mul_f32_e32 v4, 0x45800000, v5
	v_pk_add_f32 v[0:1], v[0:1], s[68:69] op_sel_hi:[1,0]
	v_cndmask_b32_e32 v4, v5, v4, vcc
	v_mul_f32_e32 v2, 0x4b800000, v1
	v_cmp_gt_f32_e32 vcc, s73, v1
	v_pk_mul_f32 v[94:95], v[108:109], v[4:5] op_sel_hi:[1,0]
	v_pk_mul_f32 v[106:107], v[106:107], v[4:5] op_sel_hi:[1,0]
	v_cndmask_b32_e32 v1, v1, v2, vcc
	v_rsq_f32_e32 v1, v1
	v_pk_mul_f32 v[104:105], v[104:105], v[4:5] op_sel_hi:[1,0]
	v_pk_mul_f32 v[48:49], v[102:103], v[4:5] op_sel_hi:[1,0]
	v_cvt_pk_bf16_f32 v4, v22, v23
	v_mul_f32_e32 v2, 0x45800000, v1
	v_cndmask_b32_e32 v2, v1, v2, vcc
	v_mul_f32_e32 v1, 0x4b800000, v0
	v_cmp_gt_f32_e32 vcc, s73, v0
	v_pk_mul_f32 v[50:51], v[50:51], v[2:3] op_sel_hi:[1,0]
	v_pk_mul_f32 v[58:59], v[42:43], v[2:3] op_sel_hi:[1,0]
	v_cndmask_b32_e32 v0, v0, v1, vcc
	v_rsq_f32_e32 v6, v0
	v_pk_mul_f32 v[56:57], v[56:57], v[2:3] op_sel_hi:[1,0]
	v_pk_mul_f32 v[0:1], v[118:119], v[2:3] op_sel_hi:[1,0]
	v_lshlrev_b32_e32 v2, 4, v88
	v_and_b32_e32 v64, 0x70, v2
	v_add_u32_e32 v67, s31, v64
	v_cvt_pk_bf16_f32 v2, v26, v27
	v_cvt_pk_bf16_f32 v3, v24, v25
	v_cvt_pk_bf16_f32 v5, v16, v17
	v_add_u32_e32 v211, v67, v40
	ds_write_b128 v211, v[2:5]
	ds_read_b32 v3, v177 offset:18432
	v_mul_f32_e32 v7, 0x45800000, v6
	v_cndmask_b32_e32 v2, v6, v7, vcc
	s_addc_u32 s23, s34, s23
	v_mov_b32_e32 v108, 0
	s_waitcnt lgkmcnt(0)
; #define GAS __attribute__((address_space(1)))
; #define LAS __attribute__((address_space(3)))
; __device__ __forceinline__ v4u pk8(const float (&a)[8], const float s) { return (v4u){pk2(a[0] * s, a[1] * s), pk2(a[2] * s, a[3] * s), pk2(a[4] * s, a[5] * s), pk2(a[6] * s, a[7] * s)}; }
; __device__ __forceinline__ void intra_item(Frame& F, const int item, LAS unsigned char* SA, LAS unsigned char* SB, LAS float* GC, LAS float* BT) {
;     ...
;     for (int r = 0; r < 8; ++r) { const int c = 8 * rg + r; *(LAS v4u*)(SA + c * STRB + cg * 16) = pk8(o[r], 1.f); *(GAS v4u*)(gi + 3 * 8192 + c * 128 + cg * 16) = pk8(o[r], __expf(gl - GC[c])); }
	v_pk_mul_f32 v[52:53], v[36:37], v[2:3] op_sel_hi:[1,0]
	v_pk_mul_f32 v[6:7], v[44:45], v[2:3] op_sel_hi:[1,0]
	v_pk_mul_f32 v[4:5], v[38:39], v[2:3] op_sel_hi:[1,0]
	v_sub_f32_e32 v3, v33, v3
	v_mul_f32_e32 v3, 0x3fb8aa3b, v3
	v_exp_f32_e32 v38, v3
	v_lshl_add_u64 v[36:37], s[22:23], 0, v[64:65]
	s_mov_b64 s[22:23], 0x6000
	v_pk_mul_f32 v[54:55], v[114:115], v[2:3] op_sel_hi:[1,0]
	v_pk_mul_f32 v[26:27], v[26:27], v[38:39] op_sel_hi:[1,0]
	v_pk_mul_f32 v[24:25], v[24:25], v[38:39] op_sel_hi:[1,0]
	v_cvt_pk_bf16_f32 v40, v26, v27
	v_cvt_pk_bf16_f32 v41, v24, v25
	v_pk_mul_f32 v[26:27], v[22:23], v[38:39] op_sel_hi:[1,0]
	v_cvt_pk_bf16_f32 v22, v14, v15
	v_cvt_pk_bf16_f32 v23, v20, v21
	v_cvt_pk_bf16_f32 v24, v18, v19
	v_cvt_pk_bf16_f32 v25, v10, v11
	ds_write_b128 v211, v[22:25] offset:144
	ds_read_b32 v22, v177 offset:18436
	v_pk_mul_f32 v[16:17], v[16:17], v[38:39] op_sel_hi:[1,0]
	v_lshlrev_b32_e32 v38, 7, v158
	v_cvt_pk_bf16_f32 v43, v16, v17
	v_lshl_add_u64 v[2:3], v[36:37], 0, s[22:23]
	s_waitcnt lgkmcnt(0)
	v_sub_f32_e32 v16, v33, v22
	v_mul_f32_e32 v16, 0x3fb8aa3b, v16
	v_exp_f32_e32 v22, v16
	v_ashrrev_i32_e32 v39, 31, v38
	v_cvt_pk_bf16_f32 v42, v26, v27
	v_lshl_add_u64 v[16:17], v[2:3], 0, v[38:39]
	global_store_dwordx4 v[16:17], v[40:43], off
	v_pk_mul_f32 v[14:15], v[14:15], v[22:23] op_sel_hi:[1,0]
	v_pk_mul_f32 v[16:17], v[20:21], v[22:23] op_sel_hi:[1,0]
	v_cvt_pk_bf16_f32 v14, v14, v15
	v_cvt_pk_bf16_f32 v15, v16, v17
	v_pk_mul_f32 v[20:21], v[18:19], v[22:23] op_sel_hi:[1,0]
	v_cvt_pk_bf16_f32 v16, v8, v9
	v_cvt_pk_bf16_f32 v17, v12, v13
	v_cvt_pk_bf16_f32 v18, v92, v93
	v_cvt_pk_bf16_f32 v19, v90, v91
	ds_write_b128 v211, v[16:19] offset:288
	ds_read_b32 v18, v177 offset:18440
	v_pk_mul_f32 v[10:11], v[10:11], v[22:23] op_sel_hi:[1,0]
	v_or_b32_e32 v40, 0x80, v38
	v_cvt_pk_bf16_f32 v17, v10, v11
	v_ashrrev_i32_e32 v41, 31, v40
	s_waitcnt lgkmcnt(0)
	v_sub_f32_e32 v10, v33, v18
	v_mul_f32_e32 v10, 0x3fb8aa3b, v10
	v_exp_f32_e32 v18, v10
	v_cvt_pk_bf16_f32 v16, v20, v21
	v_lshl_add_u64 v[10:11], v[2:3], 0, v[40:41]
	global_store_dwordx4 v[10:11], v[14:17], off
	v_pk_mul_f32 v[8:9], v[8:9], v[18:19] op_sel_hi:[1,0]
	v_pk_mul_f32 v[10:11], v[12:13], v[18:19] op_sel_hi:[1,0]
	v_cvt_pk_bf16_f32 v8, v8, v9
	v_cvt_pk_bf16_f32 v9, v10, v11
	v_cvt_pk_bf16_f32 v10, v62, v63
	v_cvt_pk_bf16_f32 v11, v60, v61
	v_cvt_pk_bf16_f32 v12, v30, v31
	v_cvt_pk_bf16_f32 v13, v28, v29
	ds_write_b128 v211, v[10:13] offset:432
	ds_read_b32 v16, v177 offset:18444
	v_pk_mul_f32 v[12:13], v[90:91], v[18:19] op_sel_hi:[1,0]
	v_pk_mul_f32 v[14:15], v[92:93], v[18:19] op_sel_hi:[1,0]
	v_cvt_pk_bf16_f32 v11, v12, v13
	v_cvt_pk_bf16_f32 v10, v14, v15
	s_waitcnt lgkmcnt(0)
	v_sub_f32_e32 v12, v33, v16
	v_mul_f32_e32 v12, 0x3fb8aa3b, v12
	v_exp_f32_e32 v14, v12
	v_or_b32_e32 v42, 0x100, v38
	v_ashrrev_i32_e32 v43, 31, v42
	v_lshl_add_u64 v[12:13], v[2:3], 0, v[42:43]
	global_store_dwordx4 v[12:13], v[8:11], off
	v_cvt_pk_bf16_f32 v12, v96, v97
	v_cvt_pk_bf16_f32 v13, v100, v101
	v_pk_mul_f32 v[8:9], v[62:63], v[14:15] op_sel_hi:[1,0]
	v_pk_mul_f32 v[10:11], v[60:61], v[14:15] op_sel_hi:[1,0]
	v_cvt_pk_bf16_f32 v8, v8, v9
	v_cvt_pk_bf16_f32 v9, v10, v11
	v_cvt_pk_bf16_f32 v10, v46, v47
	v_cvt_pk_bf16_f32 v11, v98, v99
	ds_write_b128 v211, v[10:13] offset:576
	v_pk_mul_f32 v[16:17], v[30:31], v[14:15] op_sel_hi:[1,0]
	ds_read_b32 v15, v177 offset:18448
	v_or_b32_e32 v44, 0x180, v38
	v_ashrrev_i32_e32 v45, 31, v44
	v_cvt_pk_bf16_f32 v10, v16, v17
	s_movk_i32 s22, 0x1000
	s_waitcnt lgkmcnt(0)
; #define GAS __attribute__((address_space(1)))
; #define LAS __attribute__((address_space(3)))
; __device__ __forceinline__ v4u pk8(const float (&a)[8], const float s) { return (v4u){pk2(a[0] * s, a[1] * s), pk2(a[2] * s, a[3] * s), pk2(a[4] * s, a[5] * s), pk2(a[6] * s, a[7] * s)}; }
; __device__ __forceinline__ void prep_seg(const bf16_t* QK, const float* cw, const size_t rowbase, const int t0, const int h, const int seg, const int lane, float (&o)[8][8]) {
;     const int rg = lane >> 3, cg = lane & 7, col = seg * 512 + h * 64 + cg * 8;
;     float wt[4][8];
; #pragma unroll
;     for (int j = 0; j < 4; ++j) { const f32x4 a = *(const GAS f32x4*)(cw + j * CONVD + col), b = *(const GAS f32x4*)(cw + j * CONVD + col + 4); wt[j][0] = a.x; wt[j][1] = a.y; wt[j][2] = a.z; wt[j][3] = a.w; wt[j][4] = b.x; wt[j][5] = b.y; wt[j][6] = b.z; wt[j][7] = b.w; }
; __device__ __forceinline__ void intra_item(Frame& F, const int item, LAS unsigned char* SA, LAS unsigned char* SB, LAS float* GC, LAS float* BT) {
;     ...
;     for (int r = 0; r < 8; ++r) { const int c = 8 * rg + r; *(LAS v4u*)(SA + c * STRB + cg * 16) = pk8(o[r], 1.f); *(GAS v4u*)(gi + 3 * 8192 + c * 128 + cg * 16) = pk8(o[r], __expf(gl - GC[c])); }
	v_pk_mul_f32 v[12:13], v[28:29], v[14:15] op_sel_hi:[1,0]
	v_lshlrev_b32_e32 v64, 1, v89
	v_cvt_pk_bf16_f32 v11, v12, v13
	v_sub_f32_e32 v12, v33, v15
	v_mul_f32_e32 v12, 0x3fb8aa3b, v12
	v_exp_f32_e32 v14, v12
	v_lshl_add_u64 v[12:13], v[2:3], 0, v[44:45]
	global_store_dwordx4 v[12:13], v[8:11], off
	v_cvt_pk_bf16_f32 v12, v104, v105
	v_cvt_pk_bf16_f32 v13, v48, v49
	v_pk_mul_f32 v[8:9], v[46:47], v[14:15] op_sel_hi:[1,0]
	v_pk_mul_f32 v[10:11], v[98:99], v[14:15] op_sel_hi:[1,0]
	v_cvt_pk_bf16_f32 v8, v8, v9
	v_cvt_pk_bf16_f32 v9, v10, v11
	v_cvt_pk_bf16_f32 v10, v94, v95
	v_cvt_pk_bf16_f32 v11, v106, v107
	ds_write_b128 v211, v[10:13] offset:720
	v_pk_mul_f32 v[16:17], v[96:97], v[14:15] op_sel_hi:[1,0]
	ds_read_b32 v15, v177 offset:18452
	v_or_b32_e32 v46, 0x200, v38
	v_ashrrev_i32_e32 v47, 31, v46
	v_cvt_pk_bf16_f32 v10, v16, v17
	v_lshl_add_u64 v[60:61], s[46:47], 0, v[64:65]
	s_waitcnt lgkmcnt(0)
	v_pk_mul_f32 v[12:13], v[100:101], v[14:15] op_sel_hi:[1,0]
	v_mov_b32_e32 v109, 0
	v_cvt_pk_bf16_f32 v11, v12, v13
	v_sub_f32_e32 v12, v33, v15
	v_mul_f32_e32 v12, 0x3fb8aa3b, v12
	v_exp_f32_e32 v14, v12
	v_lshl_add_u64 v[12:13], v[2:3], 0, v[46:47]
	global_store_dwordx4 v[12:13], v[8:11], off
	v_cvt_pk_bf16_f32 v12, v56, v57
	v_cvt_pk_bf16_f32 v13, v0, v1
	v_pk_mul_f32 v[8:9], v[94:95], v[14:15] op_sel_hi:[1,0]
	v_pk_mul_f32 v[10:11], v[106:107], v[14:15] op_sel_hi:[1,0]
	v_cvt_pk_bf16_f32 v8, v8, v9
	v_cvt_pk_bf16_f32 v9, v10, v11
	v_cvt_pk_bf16_f32 v10, v50, v51
	v_cvt_pk_bf16_f32 v11, v58, v59
	ds_write_b128 v211, v[10:13] offset:864
	v_pk_mul_f32 v[16:17], v[104:105], v[14:15] op_sel_hi:[1,0]
	ds_read_b32 v15, v177 offset:18456
	v_cvt_pk_bf16_f32 v10, v16, v17
	v_mov_b32_e32 v104, 0
	v_mov_b32_e32 v105, 0
	v_mov_b32_e32 v106, 0
	s_waitcnt lgkmcnt(0)
	v_pk_mul_f32 v[12:13], v[48:49], v[14:15] op_sel_hi:[1,0]
	v_or_b32_e32 v48, 0x280, v38
	v_cvt_pk_bf16_f32 v11, v12, v13
	v_sub_f32_e32 v12, v33, v15
	v_mul_f32_e32 v12, 0x3fb8aa3b, v12
	v_exp_f32_e32 v14, v12
	v_ashrrev_i32_e32 v49, 31, v48
	v_lshl_add_u64 v[12:13], v[2:3], 0, v[48:49]
	global_store_dwordx4 v[12:13], v[8:11], off
	v_pk_mul_f32 v[16:17], v[56:57], v[14:15] op_sel_hi:[1,0]
	v_cvt_pk_bf16_f32 v12, v4, v5
	v_pk_mul_f32 v[8:9], v[50:51], v[14:15] op_sel_hi:[1,0]
	v_pk_mul_f32 v[10:11], v[58:59], v[14:15] op_sel_hi:[1,0]
	v_or_b32_e32 v15, 7, v88
	v_mul_lo_u32 v18, v15, s74
	v_cvt_pk_bf16_f32 v8, v8, v9
	v_cvt_pk_bf16_f32 v9, v10, v11
	v_cvt_pk_bf16_f32 v10, v52, v53
	v_cvt_pk_bf16_f32 v11, v6, v7
	v_cvt_pk_bf16_f32 v13, v54, v55
	v_add_u32_e32 v212, v67, v18
	ds_write_b128 v212, v[10:13]
	v_lshl_add_u32 v178, v15, 2, s31
	ds_read_b32 v12, v178 offset:18432
	v_pk_mul_f32 v[0:1], v[0:1], v[14:15] op_sel_hi:[1,0]
	v_or_b32_e32 v50, 0x300, v38
	v_cvt_pk_bf16_f32 v11, v0, v1
	v_ashrrev_i32_e32 v51, 31, v50
	s_waitcnt lgkmcnt(0)
	v_sub_f32_e32 v0, v33, v12
	v_mul_f32_e32 v0, 0x3fb8aa3b, v0
	v_exp_f32_e32 v0, v0
	v_cvt_pk_bf16_f32 v10, v16, v17
	v_lshl_add_u64 v[12:13], v[2:3], 0, v[50:51]
	global_store_dwordx4 v[12:13], v[8:11], off
	v_pk_mul_f32 v[6:7], v[6:7], v[0:1] op_sel_hi:[1,0]
	v_pk_mul_f32 v[4:5], v[4:5], v[0:1] op_sel_hi:[1,0]
	v_pk_mul_f32 v[8:9], v[52:53], v[0:1] op_sel_hi:[1,0]
	v_lshlrev_b32_e32 v52, 7, v15
	v_pk_mul_f32 v[0:1], v[54:55], v[0:1] op_sel_hi:[1,0]
	v_ashrrev_i32_e32 v53, 31, v52
	v_cvt_pk_bf16_f32 v8, v8, v9
	v_cvt_pk_bf16_f32 v9, v6, v7
	v_cvt_pk_bf16_f32 v10, v4, v5
	v_cvt_pk_bf16_f32 v11, v0, v1
	v_lshl_add_u64 v[0:1], v[2:3], 0, v[52:53]
	v_add_co_u32_e32 v2, vcc, s22, v34
	global_store_dwordx4 v[0:1], v[8:11], off
	s_nop 0
	v_addc_co_u32_e32 v3, vcc, 0, v35, vcc
	s_movk_i32 s22, 0x3000
	global_load_dwordx4 v[16:19], v[34:35], off offset:16
	global_load_dwordx4 v[20:23], v[34:35], off
	v_lshl_add_u64 v[0:1], v[34:35], 0, s[44:45]
	global_load_dwordx4 v[28:31], v[2:3], off offset:2048
	global_load_dwordx4 v[24:27], v[0:1], off offset:16
	v_add_co_u32_e32 v2, vcc, s22, v34
	v_lshl_add_u64 v[0:1], v[34:35], 0, s[48:49]
	s_nop 0
	v_addc_co_u32_e32 v3, vcc, 0, v35, vcc
	global_load_dwordx4 v[12:15], v[2:3], off
	global_load_dwordx4 v[8:11], v[0:1], off offset:16
	v_add_co_u32_e32 v0, vcc, 0x4000, v34
	v_lshl_add_u64 v[4:5], v[34:35], 0, s[78:79]
	s_nop 0
	v_addc_co_u32_e32 v1, vcc, 0, v35, vcc
	global_load_dwordx4 v[0:3], v[0:1], off offset:2048
	s_nop 0
	global_load_dwordx4 v[4:7], v[4:5], off offset:16


; #define GAS __attribute__((address_space(1)))
; __device__ __forceinline__ void prep_seg(const bf16_t* QK, const float* cw, const size_t rowbase, const int t0, const int h, const int seg, const int lane, float (&o)[8][8]) {
;     ...
;     for (int rr = 0; rr < 11; ++rr) { const int t = t0 + 8 * rg + rr - 3; float x[8];
;         if (t >= 0) unpack8(*(const GAS v4u*)(QK + (rowbase + t) * CONVD + col), x); else {
; #pragma unroll
;             for (int e = 0; e < 8; ++e) x[e] = 0.f; }
	v_mov_b32_e32 v180, 0
	v_mov_b32_e32 v181, 0
	v_mov_b32_e32 v182, 0
	v_mov_b32_e32 v183, 0
	s_and_saveexec_b64 s[22:23], s[0:1]
	v_mov_b32_e32 v69, v65
	v_lshl_add_u64 v[32:33], s[82:83], 0, v[68:69]
	v_mad_u64_u32 v[34:35], s[24:25], v32, s72, v[60:61]
	v_mad_i32_i24 v35, v33, s72, v35
	global_load_dwordx4 v[180:183], v[34:35], off
.LBB0_932:
	s_or_b64 exec, exec, s[22:23]


; #define GAS __attribute__((address_space(1)))
; __device__ __forceinline__ void prep_seg(const bf16_t* QK, const float* cw, const size_t rowbase, const int t0, const int h, const int seg, const int lane, float (&o)[8][8]) {
;     ...
;     for (int rr = 0; rr < 11; ++rr) { const int t = t0 + 8 * rg + rr - 3; float x[8];
;         if (t >= 0) unpack8(*(const GAS v4u*)(QK + (rowbase + t) * CONVD + col), x); else {
; #pragma unroll
;             for (int e = 0; e < 8; ++e) x[e] = 0.f; }
	v_mov_b32_e32 v184, 0
	v_mov_b32_e32 v185, 0
	v_mov_b32_e32 v186, 0
	v_mov_b32_e32 v187, 0
	s_and_saveexec_b64 s[22:23], s[2:3]
	v_mov_b32_e32 v71, v65
	v_lshl_add_u64 v[34:35], s[82:83], 0, v[70:71]
	v_mad_u64_u32 v[54:55], s[24:25], v34, s72, v[60:61]
	v_mad_i32_i24 v55, v35, s72, v55
	global_load_dwordx4 v[184:187], v[54:55], off
.LBB0_934:
	s_or_b64 exec, exec, s[22:23]


; #define GAS __attribute__((address_space(1)))
; __device__ __forceinline__ void prep_seg(const bf16_t* QK, const float* cw, const size_t rowbase, const int t0, const int h, const int seg, const int lane, float (&o)[8][8]) {
;     ...
;     for (int rr = 0; rr < 11; ++rr) { const int t = t0 + 8 * rg + rr - 3; float x[8];
;         if (t >= 0) unpack8(*(const GAS v4u*)(QK + (rowbase + t) * CONVD + col), x); else {
; #pragma unroll
;             for (int e = 0; e < 8; ++e) x[e] = 0.f; }
	v_mov_b32_e32 v188, 0
	v_mov_b32_e32 v189, 0
	v_mov_b32_e32 v190, 0
	v_mov_b32_e32 v191, 0
	s_and_saveexec_b64 s[22:23], s[4:5]
	v_mov_b32_e32 v73, v65
	v_lshl_add_u64 v[34:35], s[82:83], 0, v[72:73]
	v_mad_u64_u32 v[54:55], s[24:25], v34, s72, v[60:61]
	v_mad_i32_i24 v55, v35, s72, v55
	global_load_dwordx4 v[188:191], v[54:55], off
.LBB0_936:
	s_or_b64 exec, exec, s[22:23]


; #define GAS __attribute__((address_space(1)))
; __device__ __forceinline__ void prep_seg(const bf16_t* QK, const float* cw, const size_t rowbase, const int t0, const int h, const int seg, const int lane, float (&o)[8][8]) {
;     ...
;     for (int rr = 0; rr < 11; ++rr) { const int t = t0 + 8 * rg + rr - 3; float x[8];
;         if (t >= 0) unpack8(*(const GAS v4u*)(QK + (rowbase + t) * CONVD + col), x); else {
; #pragma unroll
;             for (int e = 0; e < 8; ++e) x[e] = 0.f; }
	v_mov_b32_e32 v192, 0
	v_mov_b32_e32 v193, 0
	v_mov_b32_e32 v194, 0
	v_mov_b32_e32 v195, 0
	s_and_saveexec_b64 s[22:23], s[6:7]
	v_mov_b32_e32 v67, v65
	v_lshl_add_u64 v[34:35], s[82:83], 0, v[66:67]
	v_mad_u64_u32 v[54:55], s[24:25], v34, s72, v[60:61]
	v_mad_i32_i24 v55, v35, s72, v55
	global_load_dwordx4 v[192:195], v[54:55], off
.LBB0_938:
	s_or_b64 exec, exec, s[22:23]


; #define GAS __attribute__((address_space(1)))
; __device__ __forceinline__ void prep_seg(const bf16_t* QK, const float* cw, const size_t rowbase, const int t0, const int h, const int seg, const int lane, float (&o)[8][8]) {
;     ...
;     for (int rr = 0; rr < 11; ++rr) { const int t = t0 + 8 * rg + rr - 3; float x[8];
;         if (t >= 0) unpack8(*(const GAS v4u*)(QK + (rowbase + t) * CONVD + col), x); else {
; #pragma unroll
;             for (int e = 0; e < 8; ++e) x[e] = 0.f; }
	v_mov_b32_e32 v196, 0
	v_mov_b32_e32 v197, 0
	v_mov_b32_e32 v198, 0
	v_mov_b32_e32 v199, 0
	s_and_saveexec_b64 s[22:23], s[8:9]
	v_mov_b32_e32 v75, v65
	v_lshl_add_u64 v[34:35], s[82:83], 0, v[74:75]
	v_mad_u64_u32 v[54:55], s[24:25], v34, s72, v[60:61]
	v_mad_i32_i24 v55, v35, s72, v55
	global_load_dwordx4 v[196:199], v[54:55], off
.LBB0_940:
	s_or_b64 exec, exec, s[22:23]


; #define GAS __attribute__((address_space(1)))
; __device__ __forceinline__ void prep_seg(const bf16_t* QK, const float* cw, const size_t rowbase, const int t0, const int h, const int seg, const int lane, float (&o)[8][8]) {
;     ...
;     for (int rr = 0; rr < 11; ++rr) { const int t = t0 + 8 * rg + rr - 3; float x[8];
;         if (t >= 0) unpack8(*(const GAS v4u*)(QK + (rowbase + t) * CONVD + col), x); else {
; #pragma unroll
;             for (int e = 0; e < 8; ++e) x[e] = 0.f; }
	v_mov_b32_e32 v204, 0
	v_mov_b32_e32 v205, 0
	v_mov_b32_e32 v206, 0
	v_mov_b32_e32 v207, 0
	s_and_saveexec_b64 s[22:23], s[10:11]
	v_mov_b32_e32 v77, v65
	v_lshl_add_u64 v[34:35], s[82:83], 0, v[76:77]
	v_mad_u64_u32 v[54:55], s[24:25], v34, s72, v[60:61]
	v_mad_i32_i24 v55, v35, s72, v55
	global_load_dwordx4 v[204:207], v[54:55], off
.LBB0_942:
	s_or_b64 exec, exec, s[22:23]


; #define GAS __attribute__((address_space(1)))
; __device__ __forceinline__ void prep_seg(const bf16_t* QK, const float* cw, const size_t rowbase, const int t0, const int h, const int seg, const int lane, float (&o)[8][8]) {
;     ...
;     for (int rr = 0; rr < 11; ++rr) { const int t = t0 + 8 * rg + rr - 3; float x[8];
;         if (t >= 0) unpack8(*(const GAS v4u*)(QK + (rowbase + t) * CONVD + col), x); else {
; #pragma unroll
;             for (int e = 0; e < 8; ++e) x[e] = 0.f; }
	v_mov_b32_e32 v214, 0
	v_mov_b32_e32 v215, 0
	v_mov_b32_e32 v216, 0
	v_mov_b32_e32 v217, 0
	s_and_saveexec_b64 s[22:23], s[12:13]
	v_mov_b32_e32 v79, v65
	v_lshl_add_u64 v[34:35], s[82:83], 0, v[78:79]
	v_mad_u64_u32 v[54:55], s[24:25], v34, s72, v[60:61]
	v_mad_i32_i24 v55, v35, s72, v55
	global_load_dwordx4 v[214:217], v[54:55], off
.LBB0_944:
	s_or_b64 exec, exec, s[22:23]


; #define GAS __attribute__((address_space(1)))
; __device__ __forceinline__ void prep_seg(const bf16_t* QK, const float* cw, const size_t rowbase, const int t0, const int h, const int seg, const int lane, float (&o)[8][8]) {
;     ...
;     for (int rr = 0; rr < 11; ++rr) { const int t = t0 + 8 * rg + rr - 3; float x[8];
;         if (t >= 0) unpack8(*(const GAS v4u*)(QK + (rowbase + t) * CONVD + col), x); else {
; #pragma unroll
;             for (int e = 0; e < 8; ++e) x[e] = 0.f; }
	v_mov_b32_e32 v218, 0
	v_mov_b32_e32 v219, 0
	v_mov_b32_e32 v220, 0
	v_mov_b32_e32 v221, 0
	s_and_saveexec_b64 s[22:23], s[14:15]
	v_mov_b32_e32 v81, v65
	v_lshl_add_u64 v[34:35], s[82:83], 0, v[80:81]
	v_mad_u64_u32 v[54:55], s[24:25], v34, s72, v[60:61]
	v_mad_i32_i24 v55, v35, s72, v55
	global_load_dwordx4 v[218:221], v[54:55], off
.LBB0_946:
	s_or_b64 exec, exec, s[22:23]


; #define GAS __attribute__((address_space(1)))
; __device__ __forceinline__ void prep_seg(const bf16_t* QK, const float* cw, const size_t rowbase, const int t0, const int h, const int seg, const int lane, float (&o)[8][8]) {
;     ...
;     for (int rr = 0; rr < 11; ++rr) { const int t = t0 + 8 * rg + rr - 3; float x[8];
;         if (t >= 0) unpack8(*(const GAS v4u*)(QK + (rowbase + t) * CONVD + col), x); else {
; #pragma unroll
;             for (int e = 0; e < 8; ++e) x[e] = 0.f; }
	v_mov_b32_e32 v222, 0
	v_mov_b32_e32 v223, 0
	v_mov_b32_e32 v224, 0
	v_mov_b32_e32 v225, 0
	s_and_saveexec_b64 s[22:23], s[16:17]
	v_mov_b32_e32 v83, v65
	v_lshl_add_u64 v[34:35], s[82:83], 0, v[82:83]
	v_mad_u64_u32 v[54:55], s[24:25], v34, s72, v[60:61]
	v_mad_i32_i24 v55, v35, s72, v55
	global_load_dwordx4 v[222:225], v[54:55], off
.LBB0_948:
	s_or_b64 exec, exec, s[22:23]


; #define GAS __attribute__((address_space(1)))
; __device__ __forceinline__ void prep_seg(const bf16_t* QK, const float* cw, const size_t rowbase, const int t0, const int h, const int seg, const int lane, float (&o)[8][8]) {
;     ...
;     for (int rr = 0; rr < 11; ++rr) { const int t = t0 + 8 * rg + rr - 3; float x[8];
;         if (t >= 0) unpack8(*(const GAS v4u*)(QK + (rowbase + t) * CONVD + col), x); else {
; #pragma unroll
;             for (int e = 0; e < 8; ++e) x[e] = 0.f; }
	v_mov_b32_e32 v226, 0
	v_mov_b32_e32 v227, 0
	v_mov_b32_e32 v228, 0
	v_mov_b32_e32 v229, 0
	s_and_saveexec_b64 s[22:23], s[18:19]
	v_mov_b32_e32 v85, v65
	v_lshl_add_u64 v[54:55], s[82:83], 0, v[84:85]
	v_mad_u64_u32 v[56:57], s[24:25], v54, s72, v[60:61]
	v_mad_i32_i24 v57, v55, s72, v57
	global_load_dwordx4 v[226:229], v[56:57], off
.LBB0_950:
	s_or_b64 exec, exec, s[22:23]


; #define GAS __attribute__((address_space(1)))
; __device__ __forceinline__ void prep_seg(const bf16_t* QK, const float* cw, const size_t rowbase, const int t0, const int h, const int seg, const int lane, float (&o)[8][8]) {
;     ...
;     for (int rr = 0; rr < 11; ++rr) { const int t = t0 + 8 * rg + rr - 3; float x[8];
;         if (t >= 0) unpack8(*(const GAS v4u*)(QK + (rowbase + t) * CONVD + col), x); else {
; #pragma unroll
;             for (int e = 0; e < 8; ++e) x[e] = 0.f; }
	v_mov_b32_e32 v230, 0
	v_mov_b32_e32 v231, 0
	v_mov_b32_e32 v232, 0
	v_mov_b32_e32 v233, 0
	s_and_saveexec_b64 s[22:23], s[20:21]
	v_mov_b32_e32 v87, v65
	v_lshl_add_u64 v[34:35], s[82:83], 0, v[86:87]
	v_mad_u64_u32 v[54:55], s[24:25], v34, s72, v[60:61]
	v_mad_i32_i24 v55, v35, s72, v55
	global_load_dwordx4 v[230:233], v[54:55], off

; #define LAS __attribute__((address_space(3)))
; __device__ __forceinline__ unsigned pk2(float lo, float hi) { const f32x2 v = {lo, hi}; const bf16x2_t b = __builtin_convertvector(v, bf16x2_t); return __builtin_bit_cast(unsigned, b); }
; __device__ __forceinline__ void strip_mm(f32x4 (&acc)[4], const LAS unsigned char* A, const LAS unsigned char* Bt, const int r0, const int lane) {
;     const int c16 = lane & 15, q4 = lane >> 4; bf16x8 a[2], b[2][4];
; #pragma unroll
;     for (int ks = 0; ks < 2; ++ks) { a[ks] = *(const LAS bf16x8*)(A + (r0 + c16) * STRB + (32 * ks + 8 * q4) * 2);
; #pragma unroll
;         for (int tn = 0; tn < 4; ++tn) b[ks][tn] = *(const LAS bf16x8*)(Bt + (16 * tn + c16) * STRB + (32 * ks + 8 * q4) * 2); }
;     __builtin_amdgcn_sched_barrier(0);
; #pragma unroll
;     for (int ks = 0; ks < 2; ++ks)
; #pragma unroll
;         for (int tn = 0; tn < 4; ++tn) acc[tn] = __builtin_amdgcn_mfma_f32_16x16x32_bf16(a[ks], b[ks][tn], acc[tn], 0, 0, 0);
; }
; __device__ __forceinline__ void intra_item(Frame& F, const int item, LAS unsigned char* SA, LAS unsigned char* SB, LAS float* GC, LAS float* BT) {
;     ...
;     for (int st = 0; st < 4; ++st) { f32x4 acc[4]; zero4(acc); strip_mm(acc, SA, SB, 16 * st, lane);
; #pragma unroll
;         for (int tn = 0; tn < 4; ++tn) { const int c = 16 * tn + c16, s0 = 16 * st + 4 * q4; const float gcc = GC[c]; float v[4];
; #pragma unroll
;             for (int i = 0; i < 4; ++i) v[i] = (c >= s0 + i) ? acc[tn][i] * __expf(gcc - GC[s0 + i]) : 0.f;
;             st8_pair16(gi + 8192 + c * 128 + s0 * 2, (u32x2){pk2(v[0], v[1]), pk2(v[2], v[3])}, evenrow, sel); } }
.LBB0_954:
	ds_read_b128 v[100:103], v29
	ds_read_b128 v[0:3], v28
	ds_read_b128 v[38:41], v28 offset:64
	ds_read_b128 v[4:7], v27 offset:9216
	ds_read_b128 v[8:11], v27 offset:9280
	ds_read_b128 v[12:15], v27 offset:11520
	ds_read_b128 v[34:37], v27 offset:11584
	ds_read_b128 v[42:45], v27 offset:13824
	ds_read_b128 v[46:49], v27 offset:13888
	ds_read_b128 v[50:53], v27 offset:16128
	ds_read_b128 v[54:57], v27 offset:16192
	s_waitcnt lgkmcnt(7)
	v_mfma_f32_16x16x32_bf16 v[4:7], v[0:3], v[4:7], 0
	v_add_u32_e32 v31, s36, v22
	v_cmp_ge_i32_e32 vcc, v67, v31
	s_waitcnt lgkmcnt(5)
	v_mfma_f32_16x16x32_bf16 v[58:61], v[0:3], v[12:15], 0
	s_waitcnt lgkmcnt(3)
	v_mfma_f32_16x16x32_bf16 v[42:45], v[0:3], v[42:45], 0
	s_waitcnt lgkmcnt(1)
	v_mfma_f32_16x16x32_bf16 v[0:3], v[0:3], v[50:53], 0
	v_mfma_f32_16x16x32_bf16 v[12:15], v[38:41], v[8:11], v[4:7]
	v_mfma_f32_16x16x32_bf16 v[8:11], v[38:41], v[34:37], v[58:61]
	ds_read_b32 v36, v23 offset:18432
	ds_read_b32 v104, v23 offset:18496
	ds_read_b32 v105, v23 offset:18560
	ds_read_b32 v106, v23 offset:18624
	v_mov_b32_e32 v35, 0
	v_mov_b32_e32 v37, 0
	v_mfma_f32_16x16x32_bf16 v[4:7], v[38:41], v[46:49], v[42:45]
	s_waitcnt lgkmcnt(4)
	v_mfma_f32_16x16x32_bf16 v[0:3], v[38:41], v[54:57], v[0:3]
	s_and_saveexec_b64 s[92:93], vcc
	s_cbranch_execz .LBB0_956
	s_waitcnt lgkmcnt(0)
	v_sub_f32_e32 v33, v36, v100
	v_mul_f32_e32 v33, 0x3fb8aa3b, v33
	v_exp_f32_e32 v33, v33
	s_nop 0
	v_mul_f32_e32 v37, v12, v33
.LBB0_956:
	s_or_b64 exec, exec, s[92:93]
	v_cmp_gt_i32_e32 vcc, v67, v31
	v_mov_b32_e32 v12, 0
	s_and_saveexec_b64 s[92:93], vcc
	s_cbranch_execz .LBB0_958
	s_waitcnt lgkmcnt(0)
	v_sub_f32_e32 v12, v36, v101
	v_mul_f32_e32 v12, 0x3fb8aa3b, v12
	v_exp_f32_e32 v12, v12
	s_nop 0
	v_mul_f32_e32 v12, v13, v12
.LBB0_958:
	s_or_b64 exec, exec, s[92:93]
	v_add_u32_e32 v33, 2, v31
	v_cmp_ge_i32_e32 vcc, v67, v33
	s_and_saveexec_b64 s[92:93], vcc
	s_cbranch_execz .LBB0_960
	s_waitcnt lgkmcnt(0)
	v_sub_f32_e32 v13, v36, v102
	v_mul_f32_e32 v13, 0x3fb8aa3b, v13
	v_exp_f32_e32 v13, v13
	s_nop 0
	v_mul_f32_e32 v35, v14, v13
.LBB0_960:
	s_or_b64 exec, exec, s[92:93]
	v_add_u32_e32 v34, 3, v31
	v_cmp_ge_i32_e32 vcc, v67, v34
	v_mov_b32_e32 v13, 0
	s_and_saveexec_b64 s[92:93], vcc
	s_cbranch_execz .LBB0_962
	s_waitcnt lgkmcnt(0)
	v_sub_f32_e32 v13, v36, v103
	v_mul_f32_e32 v13, 0x3fb8aa3b, v13
	v_exp_f32_e32 v13, v13
	s_nop 0
	v_mul_f32_e32 v13, v15, v13

; __device__ __forceinline__ unsigned pk2(float lo, float hi) { const f32x2 v = {lo, hi}; const bf16x2_t b = __builtin_convertvector(v, bf16x2_t); return __builtin_bit_cast(unsigned, b); }
; __device__ __forceinline__ void intra_item(Frame& F, const int item, LAS unsigned char* SA, LAS unsigned char* SB, LAS float* GC, LAS float* BT) {
;     ...
;     for (int st = 0; st < 4; ++st) { f32x4 acc[4]; zero4(acc); strip_mm(acc, SA, SB, 16 * st, lane);
; #pragma unroll
;         for (int tn = 0; tn < 4; ++tn) { const int c = 16 * tn + c16, s0 = 16 * st + 4 * q4; const float gcc = GC[c]; float v[4];
; #pragma unroll
;             for (int i = 0; i < 4; ++i) v[i] = (c >= s0 + i) ? acc[tn][i] * __expf(gcc - GC[s0 + i]) : 0.f;
;             st8_pair16(gi + 8192 + c * 128 + s0 * 2, (u32x2){pk2(v[0], v[1]), pk2(v[2], v[3])}, evenrow, sel); } }
.LBB0_964:
	s_or_b64 exec, exec, s[92:93]
	v_cmp_ge_i32_e32 vcc, v24, v31
	v_mov_b32_e32 v12, 0
	v_mov_b32_e32 v14, 0
	s_and_saveexec_b64 s[92:93], vcc
	s_cbranch_execz .LBB0_966
	s_waitcnt lgkmcnt(0)
	v_sub_f32_e32 v14, v104, v100
	v_mul_f32_e32 v14, 0x3fb8aa3b, v14
	v_exp_f32_e32 v14, v14
	s_nop 0
	v_mul_f32_e32 v14, v8, v14
.LBB0_966:
	s_or_b64 exec, exec, s[92:93]
	v_cmp_gt_i32_e32 vcc, v24, v31
	s_and_saveexec_b64 s[92:93], vcc
	s_cbranch_execz .LBB0_968
	s_waitcnt lgkmcnt(0)
	v_sub_f32_e32 v8, v104, v101
	v_mul_f32_e32 v8, 0x3fb8aa3b, v8
	v_exp_f32_e32 v8, v8
	s_nop 0
	v_mul_f32_e32 v12, v9, v8
.LBB0_968:
	s_or_b64 exec, exec, s[92:93]
	v_cmp_ge_i32_e32 vcc, v24, v33
	v_mov_b32_e32 v9, 0
	v_mov_b32_e32 v15, 0
	s_and_saveexec_b64 s[92:93], vcc
	s_cbranch_execz .LBB0_970
	s_waitcnt lgkmcnt(0)
	v_sub_f32_e32 v8, v104, v102
	v_mul_f32_e32 v8, 0x3fb8aa3b, v8
	v_exp_f32_e32 v8, v8
	s_nop 0
	v_mul_f32_e32 v15, v10, v8
.LBB0_970:
	s_or_b64 exec, exec, s[92:93]
	v_cmp_ge_i32_e32 vcc, v24, v34
	s_and_saveexec_b64 s[92:93], vcc
	s_cbranch_execz .LBB0_972
	s_waitcnt lgkmcnt(0)
	v_sub_f32_e32 v8, v104, v103
	v_mul_f32_e32 v8, 0x3fb8aa3b, v8
	v_exp_f32_e32 v8, v8
	s_nop 0
	v_mul_f32_e32 v9, v11, v8

; __device__ __forceinline__ unsigned pk2(float lo, float hi) { const f32x2 v = {lo, hi}; const bf16x2_t b = __builtin_convertvector(v, bf16x2_t); return __builtin_bit_cast(unsigned, b); }
; __device__ __forceinline__ void intra_item(Frame& F, const int item, LAS unsigned char* SA, LAS unsigned char* SB, LAS float* GC, LAS float* BT) {
;     ...
;     for (int st = 0; st < 4; ++st) { f32x4 acc[4]; zero4(acc); strip_mm(acc, SA, SB, 16 * st, lane);
; #pragma unroll
;         for (int tn = 0; tn < 4; ++tn) { const int c = 16 * tn + c16, s0 = 16 * st + 4 * q4; const float gcc = GC[c]; float v[4];
; #pragma unroll
;             for (int i = 0; i < 4; ++i) v[i] = (c >= s0 + i) ? acc[tn][i] * __expf(gcc - GC[s0 + i]) : 0.f;
;             st8_pair16(gi + 8192 + c * 128 + s0 * 2, (u32x2){pk2(v[0], v[1]), pk2(v[2], v[3])}, evenrow, sel); } }
.LBB0_974:
	s_or_b64 exec, exec, s[92:93]
	v_cmp_ge_i32_e32 vcc, v25, v31
	v_mov_b32_e32 v8, 0
	v_mov_b32_e32 v10, 0
	s_and_saveexec_b64 s[92:93], vcc
	s_cbranch_execz .LBB0_976
	s_waitcnt lgkmcnt(0)
	v_sub_f32_e32 v10, v105, v100
	v_mul_f32_e32 v10, 0x3fb8aa3b, v10
	v_exp_f32_e32 v10, v10
	s_nop 0
	v_mul_f32_e32 v10, v4, v10
.LBB0_976:
	s_or_b64 exec, exec, s[92:93]
	v_cmp_gt_i32_e32 vcc, v25, v31
	s_and_saveexec_b64 s[92:93], vcc
	s_cbranch_execz .LBB0_978
	s_waitcnt lgkmcnt(0)
	v_sub_f32_e32 v4, v105, v101
	v_mul_f32_e32 v4, 0x3fb8aa3b, v4
	v_exp_f32_e32 v4, v4
	s_nop 0
	v_mul_f32_e32 v8, v5, v4
.LBB0_978:
	s_or_b64 exec, exec, s[92:93]
	v_cmp_ge_i32_e32 vcc, v25, v33
	v_mov_b32_e32 v5, 0
	v_mov_b32_e32 v11, 0
	s_and_saveexec_b64 s[92:93], vcc
	s_cbranch_execz .LBB0_980
	s_waitcnt lgkmcnt(0)
	v_sub_f32_e32 v4, v105, v102
	v_mul_f32_e32 v4, 0x3fb8aa3b, v4
	v_exp_f32_e32 v4, v4
	s_nop 0
	v_mul_f32_e32 v11, v6, v4
.LBB0_980:
	s_or_b64 exec, exec, s[92:93]
	v_cmp_ge_i32_e32 vcc, v25, v34
	s_and_saveexec_b64 s[92:93], vcc
	s_cbranch_execz .LBB0_982
	s_waitcnt lgkmcnt(0)
	v_sub_f32_e32 v4, v105, v103
	v_mul_f32_e32 v4, 0x3fb8aa3b, v4
	v_exp_f32_e32 v4, v4
	s_nop 0
	v_mul_f32_e32 v5, v7, v4

; __device__ __forceinline__ unsigned pk2(float lo, float hi) { const f32x2 v = {lo, hi}; const bf16x2_t b = __builtin_convertvector(v, bf16x2_t); return __builtin_bit_cast(unsigned, b); }
; __device__ __forceinline__ void intra_item(Frame& F, const int item, LAS unsigned char* SA, LAS unsigned char* SB, LAS float* GC, LAS float* BT) {
;     ...
;     for (int st = 0; st < 4; ++st) { f32x4 acc[4]; zero4(acc); strip_mm(acc, SA, SB, 16 * st, lane);
; #pragma unroll
;         for (int tn = 0; tn < 4; ++tn) { const int c = 16 * tn + c16, s0 = 16 * st + 4 * q4; const float gcc = GC[c]; float v[4];
; #pragma unroll
;             for (int i = 0; i < 4; ++i) v[i] = (c >= s0 + i) ? acc[tn][i] * __expf(gcc - GC[s0 + i]) : 0.f;
;             st8_pair16(gi + 8192 + c * 128 + s0 * 2, (u32x2){pk2(v[0], v[1]), pk2(v[2], v[3])}, evenrow, sel); } }
.LBB0_984:
	s_or_b64 exec, exec, s[92:93]
	v_cmp_ge_i32_e32 vcc, v26, v31
	v_mov_b32_e32 v4, 0
	v_mov_b32_e32 v6, 0
	s_and_saveexec_b64 s[92:93], vcc
	s_cbranch_execz .LBB0_986
	s_waitcnt lgkmcnt(0)
	v_sub_f32_e32 v6, v106, v100
	v_mul_f32_e32 v6, 0x3fb8aa3b, v6
	v_exp_f32_e32 v6, v6
	s_nop 0
	v_mul_f32_e32 v6, v0, v6
.LBB0_986:
	s_or_b64 exec, exec, s[92:93]
	v_cmp_gt_i32_e32 vcc, v26, v31
	s_and_saveexec_b64 s[92:93], vcc
	s_cbranch_execz .LBB0_988
	s_waitcnt lgkmcnt(0)
	v_sub_f32_e32 v0, v106, v101
	v_mul_f32_e32 v0, 0x3fb8aa3b, v0
	v_exp_f32_e32 v0, v0
	s_nop 0
	v_mul_f32_e32 v4, v1, v0
.LBB0_988:
	s_or_b64 exec, exec, s[92:93]
	v_cmp_ge_i32_e32 vcc, v26, v33
	v_mov_b32_e32 v1, 0
	v_mov_b32_e32 v7, 0
	s_and_saveexec_b64 s[92:93], vcc
	s_cbranch_execz .LBB0_990
	s_waitcnt lgkmcnt(0)
	v_sub_f32_e32 v0, v106, v102
	v_mul_f32_e32 v0, 0x3fb8aa3b, v0
	v_exp_f32_e32 v0, v0
	s_nop 0
	v_mul_f32_e32 v7, v2, v0
.LBB0_990:
	s_or_b64 exec, exec, s[92:93]
	v_cmp_ge_i32_e32 vcc, v26, v34
	s_and_saveexec_b64 s[92:93], vcc
	s_cbranch_execz .LBB0_992
	s_waitcnt lgkmcnt(0)
	v_sub_f32_e32 v0, v106, v103
	v_mul_f32_e32 v0, 0x3fb8aa3b, v0
	v_exp_f32_e32 v0, v0
	s_nop 0
	v_mul_f32_e32 v1, v3, v0

; #define LAS __attribute__((address_space(3)))
; __device__ __forceinline__ void strip_mm(f32x4 (&acc)[4], const LAS unsigned char* A, const LAS unsigned char* Bt, const int r0, const int lane) {
;     const int c16 = lane & 15, q4 = lane >> 4; bf16x8 a[2], b[2][4];
; #pragma unroll
;     for (int ks = 0; ks < 2; ++ks) { a[ks] = *(const LAS bf16x8*)(A + (r0 + c16) * STRB + (32 * ks + 8 * q4) * 2);
; #pragma unroll
;         for (int tn = 0; tn < 4; ++tn) b[ks][tn] = *(const LAS bf16x8*)(Bt + (16 * tn + c16) * STRB + (32 * ks + 8 * q4) * 2); }
;     __builtin_amdgcn_sched_barrier(0);
; #pragma unroll
;     for (int ks = 0; ks < 2; ++ks)
; #pragma unroll
;         for (int tn = 0; tn < 4; ++tn) acc[tn] = __builtin_amdgcn_mfma_f32_16x16x32_bf16(a[ks], b[ks][tn], acc[tn], 0, 0, 0);
; }
; __device__ __forceinline__ void intra_item(Frame& F, const int item, LAS unsigned char* SA, LAS unsigned char* SB, LAS float* GC, LAS float* BT) {
;     ...
;     for (int st = 0; st < 4; ++st) { f32x4 acc[4]; zero4(acc); strip_mm(acc, SA, SA, 16 * st, lane);
; #pragma unroll
;         for (int tn = 0; tn < 4; ++tn) { const int bb = 16 * tn + c16, k0 = 16 * st + 4 * q4; const float gb = GC[bb], btb = BT[bb];
;             if (k0 < lr_n(bb)) { f32x4 v;
; #pragma unroll
;                 for (int i = 0; i < 4; ++i) v[i] = (k0 + i < bb) ? btb * acc[tn][i] * __expf(gb - GC[k0 + i]) : 0.f;
;                 *(LAS f32x4*)(SB + (lr_off(bb) + k0) * 4) = v; } } }
.LBB0_997:
	v_add_u32_e32 v107, s30, v31
	ds_read_b128 v[100:103], v107
	v_add_u32_e32 v4, s30, v30
	ds_read_b128 v[0:3], v4
	ds_read_b128 v[38:41], v4 offset:64
	ds_read_b128 v[4:7], v27
	s_waitcnt lgkmcnt(4)
	ds_read_b128 v[8:11], v27 offset:64
	ds_read_b128 v[12:15], v27 offset:2304
	ds_read_b128 v[42:45], v27 offset:2368
	ds_read_b128 v[16:19], v27 offset:4608
	ds_read_b128 v[46:49], v27 offset:4672
	ds_read_b128 v[50:53], v27 offset:6912
	ds_read_b128 v[54:57], v27 offset:6976
	s_waitcnt lgkmcnt(7)
	v_mfma_f32_16x16x32_bf16 v[4:7], v[0:3], v[4:7], 0
	v_add_u32_e32 v36, s28, v22
	v_cmp_lt_i32_e32 vcc, v36, v20
	s_waitcnt lgkmcnt(5)
	v_mfma_f32_16x16x32_bf16 v[58:61], v[0:3], v[12:15], 0
	s_waitcnt lgkmcnt(3)
	v_mfma_f32_16x16x32_bf16 v[92:95], v[0:3], v[16:19], 0
	s_waitcnt lgkmcnt(1)
	v_mfma_f32_16x16x32_bf16 v[0:3], v[0:3], v[50:53], 0
	v_mfma_f32_16x16x32_bf16 v[14:17], v[38:41], v[8:11], v[4:7]
	v_mfma_f32_16x16x32_bf16 v[8:11], v[38:41], v[42:45], v[58:61]
	v_mfma_f32_16x16x32_bf16 v[4:7], v[38:41], v[46:49], v[92:95]
	s_waitcnt lgkmcnt(0)
	v_mfma_f32_16x16x32_bf16 v[0:3], v[38:41], v[54:57], v[0:3]
	s_and_saveexec_b64 s[92:93], vcc
	s_cbranch_execz .LBB0_1017
	ds_read2st64_b32 v[18:19], v23 offset0:72 offset1:73
	v_cmp_lt_i32_e32 vcc, v36, v67
	v_mov_b32_e32 v13, 0
	v_mov_b32_e32 v12, 0
	s_and_saveexec_b64 s[94:95], vcc
	s_cbranch_execz .LBB0_1000
	s_waitcnt lgkmcnt(0)
	v_mul_f32_e32 v14, v14, v19
	s_waitcnt lgkmcnt(0)
	v_sub_f32_e32 v12, v18, v100
	v_mul_f32_e32 v12, 0x3fb8aa3b, v12
	v_exp_f32_e32 v12, v12
	s_nop 0
	v_mul_f32_e32 v12, v14, v12
.LBB0_1000:
	s_or_b64 exec, exec, s[94:95]
	v_add_u32_e32 v14, 1, v36
	v_cmp_lt_i32_e32 vcc, v14, v67
	s_and_saveexec_b64 s[94:95], vcc
	s_cbranch_execz .LBB0_1002
	s_waitcnt lgkmcnt(0)
	v_mul_f32_e32 v14, v15, v19
	s_waitcnt lgkmcnt(0)
	v_sub_f32_e32 v13, v18, v101
	v_mul_f32_e32 v13, 0x3fb8aa3b, v13
	v_exp_f32_e32 v13, v13
	s_nop 0
	v_mul_f32_e32 v13, v14, v13
.LBB0_1002:
	s_or_b64 exec, exec, s[94:95]
	v_add_u32_e32 v14, 2, v36
	v_cmp_lt_i32_e32 vcc, v14, v67
	v_mov_b32_e32 v15, 0
	v_mov_b32_e32 v14, 0
	s_and_saveexec_b64 s[94:95], vcc
	s_cbranch_execz .LBB0_1004
	s_waitcnt lgkmcnt(0)
	v_mul_f32_e32 v16, v16, v19
	s_waitcnt lgkmcnt(0)
	v_sub_f32_e32 v14, v18, v102
	v_mul_f32_e32 v14, 0x3fb8aa3b, v14
	v_exp_f32_e32 v14, v14
	s_nop 0
	v_mul_f32_e32 v14, v16, v14
.LBB0_1004:
	s_or_b64 exec, exec, s[94:95]
	v_add_u32_e32 v16, 3, v36
	v_cmp_lt_i32_e32 vcc, v16, v67
	s_and_saveexec_b64 s[94:95], vcc
	s_cbranch_execz .LBB0_1006
	s_waitcnt lgkmcnt(0)
	v_mul_f32_e32 v15, v17, v19
	s_waitcnt lgkmcnt(0)
	v_sub_f32_e32 v16, v18, v103
	v_mul_f32_e32 v16, 0x3fb8aa3b, v16
	v_exp_f32_e32 v16, v16
	s_nop 0
	v_mul_f32_e32 v15, v15, v16

; #define LAS __attribute__((address_space(3)))
; __device__ __forceinline__ void intra_item(Frame& F, const int item, LAS unsigned char* SA, LAS unsigned char* SB, LAS float* GC, LAS float* BT) {
;     ...
;     for (int st = 0; st < 4; ++st) { f32x4 acc[4]; zero4(acc); strip_mm(acc, SA, SA, 16 * st, lane);
; #pragma unroll
;         for (int tn = 0; tn < 4; ++tn) { const int bb = 16 * tn + c16, k0 = 16 * st + 4 * q4; const float gb = GC[bb], btb = BT[bb];
;             if (k0 < lr_n(bb)) { f32x4 v;
; #pragma unroll
;                 for (int i = 0; i < 4; ++i) v[i] = (k0 + i < bb) ? btb * acc[tn][i] * __expf(gb - GC[k0 + i]) : 0.f;
;                 *(LAS f32x4*)(SB + (lr_off(bb) + k0) * 4) = v; } } }
.LBB0_1008:
	v_add_u32_e32 v8, 0x80, v23
	ds_read2st64_b32 v[12:13], v8 offset0:72 offset1:73
	v_cmp_lt_i32_e32 vcc, v36, v25
	v_mov_b32_e32 v9, 0
	v_mov_b32_e32 v8, 0
	s_and_saveexec_b64 s[94:95], vcc
	s_cbranch_execz .LBB0_1010
	s_waitcnt lgkmcnt(0)
	v_mul_f32_e32 v4, v4, v13
	s_waitcnt lgkmcnt(0)
	v_sub_f32_e32 v8, v12, v100
	v_mul_f32_e32 v8, 0x3fb8aa3b, v8
	v_exp_f32_e32 v8, v8
	s_nop 0
	v_mul_f32_e32 v8, v4, v8
.LBB0_1010:
	s_or_b64 exec, exec, s[94:95]
	v_add_u32_e32 v4, 1, v36
	v_cmp_lt_i32_e32 vcc, v4, v25
	s_and_saveexec_b64 s[94:95], vcc
	s_cbranch_execz .LBB0_1012
	s_waitcnt lgkmcnt(0)
	v_mul_f32_e32 v5, v5, v13
	s_waitcnt lgkmcnt(0)
	v_sub_f32_e32 v4, v12, v101
	v_mul_f32_e32 v4, 0x3fb8aa3b, v4
	v_exp_f32_e32 v4, v4
	s_nop 0
	v_mul_f32_e32 v9, v5, v4
.LBB0_1012:
	s_or_b64 exec, exec, s[94:95]
	v_add_u32_e32 v4, 2, v36
	v_cmp_lt_i32_e32 vcc, v4, v25
	v_mov_b32_e32 v11, 0
	v_mov_b32_e32 v10, 0
	s_and_saveexec_b64 s[94:95], vcc
	s_cbranch_execz .LBB0_1014
	s_waitcnt lgkmcnt(0)
	v_mul_f32_e32 v5, v6, v13
	s_waitcnt lgkmcnt(0)
	v_sub_f32_e32 v4, v12, v102
	v_mul_f32_e32 v4, 0x3fb8aa3b, v4
	v_exp_f32_e32 v4, v4
	s_nop 0
	v_mul_f32_e32 v10, v5, v4
.LBB0_1014:
	s_or_b64 exec, exec, s[94:95]
	v_add_u32_e32 v4, 3, v36
	v_cmp_lt_i32_e32 vcc, v4, v25
	s_and_saveexec_b64 s[94:95], vcc
	s_cbranch_execz .LBB0_1016
	s_waitcnt lgkmcnt(0)
	v_mul_f32_e32 v4, v7, v13
	s_waitcnt lgkmcnt(0)
	v_sub_f32_e32 v5, v12, v103
	v_mul_f32_e32 v5, 0x3fb8aa3b, v5
	v_exp_f32_e32 v5, v5
	s_nop 0
	v_mul_f32_e32 v11, v4, v5

; #define LAS __attribute__((address_space(3)))
; __device__ __forceinline__ void intra_item(Frame& F, const int item, LAS unsigned char* SA, LAS unsigned char* SB, LAS float* GC, LAS float* BT) {
;     ...
;     for (int st = 0; st < 4; ++st) { f32x4 acc[4]; zero4(acc); strip_mm(acc, SA, SA, 16 * st, lane);
; #pragma unroll
;         for (int tn = 0; tn < 4; ++tn) { const int bb = 16 * tn + c16, k0 = 16 * st + 4 * q4; const float gb = GC[bb], btb = BT[bb];
;             if (k0 < lr_n(bb)) { f32x4 v;
; #pragma unroll
;                 for (int i = 0; i < 4; ++i) v[i] = (k0 + i < bb) ? btb * acc[tn][i] * __expf(gb - GC[k0 + i]) : 0.f;
;                 *(LAS f32x4*)(SB + (lr_off(bb) + k0) * 4) = v; } } }
.LBB0_1018:
	v_add_u32_e32 v12, 64, v23
	ds_read2st64_b32 v[16:17], v12 offset0:72 offset1:73
	v_cmp_lt_i32_e32 vcc, v36, v24
	v_mov_b32_e32 v13, 0
	v_mov_b32_e32 v12, 0
	s_and_saveexec_b64 s[94:95], vcc
	s_cbranch_execz .LBB0_1020
	s_waitcnt lgkmcnt(0)
	v_mul_f32_e32 v8, v8, v17
	s_waitcnt lgkmcnt(0)
	v_sub_f32_e32 v12, v16, v100
	v_mul_f32_e32 v12, 0x3fb8aa3b, v12
	v_exp_f32_e32 v12, v12
	s_nop 0
	v_mul_f32_e32 v12, v8, v12
.LBB0_1020:
	s_or_b64 exec, exec, s[94:95]
	v_add_u32_e32 v8, 1, v36
	v_cmp_lt_i32_e32 vcc, v8, v24
	s_and_saveexec_b64 s[94:95], vcc
	s_cbranch_execz .LBB0_1022
	s_waitcnt lgkmcnt(0)
	v_mul_f32_e32 v9, v9, v17
	s_waitcnt lgkmcnt(0)
	v_sub_f32_e32 v8, v16, v101
	v_mul_f32_e32 v8, 0x3fb8aa3b, v8
	v_exp_f32_e32 v8, v8
	s_nop 0
	v_mul_f32_e32 v13, v9, v8
.LBB0_1022:
	s_or_b64 exec, exec, s[94:95]
	v_add_u32_e32 v8, 2, v36
	v_cmp_lt_i32_e32 vcc, v8, v24
	v_mov_b32_e32 v15, 0
	v_mov_b32_e32 v14, 0
	s_and_saveexec_b64 s[94:95], vcc
	s_cbranch_execz .LBB0_1024
	s_waitcnt lgkmcnt(0)
	v_mul_f32_e32 v9, v10, v17
	s_waitcnt lgkmcnt(0)
	v_sub_f32_e32 v8, v16, v102
	v_mul_f32_e32 v8, 0x3fb8aa3b, v8
	v_exp_f32_e32 v8, v8
	s_nop 0
	v_mul_f32_e32 v14, v9, v8
.LBB0_1024:
	s_or_b64 exec, exec, s[94:95]
	v_add_u32_e32 v8, 3, v36
	v_cmp_lt_i32_e32 vcc, v8, v24
	s_and_saveexec_b64 s[94:95], vcc
	s_cbranch_execz .LBB0_1026
	s_waitcnt lgkmcnt(0)
	v_mul_f32_e32 v8, v11, v17
	s_waitcnt lgkmcnt(0)
	v_sub_f32_e32 v9, v16, v103
	v_mul_f32_e32 v9, 0x3fb8aa3b, v9
	v_exp_f32_e32 v9, v9
	s_nop 0
	v_mul_f32_e32 v15, v8, v9

; #define LAS __attribute__((address_space(3)))
; __device__ __forceinline__ void intra_item(Frame& F, const int item, LAS unsigned char* SA, LAS unsigned char* SB, LAS float* GC, LAS float* BT) {
;     ...
;     for (int st = 0; st < 4; ++st) { f32x4 acc[4]; zero4(acc); strip_mm(acc, SA, SA, 16 * st, lane);
; #pragma unroll
;         for (int tn = 0; tn < 4; ++tn) { const int bb = 16 * tn + c16, k0 = 16 * st + 4 * q4; const float gb = GC[bb], btb = BT[bb];
;             if (k0 < lr_n(bb)) { f32x4 v;
; #pragma unroll
;                 for (int i = 0; i < 4; ++i) v[i] = (k0 + i < bb) ? btb * acc[tn][i] * __expf(gb - GC[k0 + i]) : 0.f;
;                 *(LAS f32x4*)(SB + (lr_off(bb) + k0) * 4) = v; } } }
.LBB0_1028:
	v_add_u32_e32 v4, 0xc0, v23
	ds_read2st64_b32 v[8:9], v4 offset0:72 offset1:73
	v_cmp_lt_i32_e32 vcc, v36, v26
	v_mov_b32_e32 v5, 0
	v_add_u32_e32 v10, s30, v31
	v_mov_b32_e32 v4, 0
	s_and_saveexec_b64 s[94:95], vcc
	s_cbranch_execz .LBB0_1030
	s_waitcnt lgkmcnt(0)
	v_mul_f32_e32 v0, v0, v9
	s_waitcnt lgkmcnt(0)
	v_sub_f32_e32 v4, v8, v100
	v_mul_f32_e32 v4, 0x3fb8aa3b, v4
	v_exp_f32_e32 v4, v4
	s_nop 0
	v_mul_f32_e32 v4, v0, v4
.LBB0_1030:
	s_or_b64 exec, exec, s[94:95]
	v_add_u32_e32 v0, 1, v36
	v_cmp_lt_i32_e32 vcc, v0, v26
	s_and_saveexec_b64 s[94:95], vcc
	s_cbranch_execz .LBB0_1032
	s_waitcnt lgkmcnt(0)
	v_mul_f32_e32 v1, v1, v9
	s_waitcnt lgkmcnt(0)
	v_sub_f32_e32 v0, v8, v101
	v_mul_f32_e32 v0, 0x3fb8aa3b, v0
	v_exp_f32_e32 v0, v0
	s_nop 0
	v_mul_f32_e32 v5, v1, v0
.LBB0_1032:
	s_or_b64 exec, exec, s[94:95]
	v_add_u32_e32 v0, 2, v36
	v_cmp_lt_i32_e32 vcc, v0, v26
	v_mov_b32_e32 v7, 0
	v_mov_b32_e32 v6, 0
	s_and_saveexec_b64 s[94:95], vcc
	s_cbranch_execz .LBB0_1034
	s_waitcnt lgkmcnt(0)
	v_mul_f32_e32 v1, v2, v9
	s_waitcnt lgkmcnt(0)
	v_sub_f32_e32 v0, v8, v102
	v_mul_f32_e32 v0, 0x3fb8aa3b, v0
	v_exp_f32_e32 v0, v0
	s_nop 0
	v_mul_f32_e32 v6, v1, v0
.LBB0_1034:
	s_or_b64 exec, exec, s[94:95]
	v_add_u32_e32 v0, 3, v36
	v_cmp_lt_i32_e32 vcc, v0, v26
	s_and_saveexec_b64 s[94:95], vcc
	s_cbranch_execz .LBB0_995
	s_waitcnt lgkmcnt(0)
	v_mul_f32_e32 v1, v3, v9
	s_waitcnt lgkmcnt(0)
	v_sub_f32_e32 v0, v8, v103
	v_mul_f32_e32 v0, 0x3fb8aa3b, v0
	v_exp_f32_e32 v0, v0
	s_nop 0
	v_mul_f32_e32 v7, v1, v0
	s_branch .LBB0_995

; #define GAS __attribute__((address_space(1)))
; __device__ __forceinline__ void prep_seg(const bf16_t* QK, const float* cw, const size_t rowbase, const int t0, const int h, const int seg, const int lane, float (&o)[8][8]) {
;     const int rg = lane >> 3, cg = lane & 7, col = seg * 512 + h * 64 + cg * 8;
;     float wt[4][8];
; #pragma unroll
;     for (int j = 0; j < 4; ++j) { const f32x4 a = *(const GAS f32x4*)(cw + j * CONVD + col), b = *(const GAS f32x4*)(cw + j * CONVD + col + 4); wt[j][0] = a.x; wt[j][1] = a.y; wt[j][2] = a.z; wt[j][3] = a.w; wt[j][4] = b.x; wt[j][5] = b.y; wt[j][6] = b.z; wt[j][7] = b.w; }
.LBB0_1046:
	v_or_b32_e32 v67, 0x400, v89
	v_lshlrev_b32_e32 v0, 2, v67
	v_mov_b32_e32 v1, v65
	v_lshl_add_u64 v[2:3], s[70:71], 0, v[0:1]
	v_add_co_u32_e32 v4, vcc, 0x1000, v2
	global_load_dwordx4 v[8:11], v0, s[70:71] offset:16
	global_load_dwordx4 v[20:23], v0, s[70:71]
	v_addc_co_u32_e32 v5, vcc, 0, v3, vcc
	v_lshl_add_u64 v[0:1], v[2:3], 0, s[44:45]
	global_load_dwordx4 v[16:19], v[4:5], off offset:2048
	global_load_dwordx4 v[12:15], v[0:1], off offset:16
	v_add_co_u32_e32 v4, vcc, 0x3000, v2
	v_lshl_add_u64 v[0:1], v[2:3], 0, s[48:49]
	s_nop 0
	v_addc_co_u32_e32 v5, vcc, 0, v3, vcc
	global_load_dwordx4 v[28:31], v[4:5], off
	global_load_dwordx4 v[24:27], v[0:1], off offset:16
	v_lshl_add_u64 v[0:1], v[2:3], 0, s[78:79]
	v_add_co_u32_e32 v2, vcc, 0x4000, v2

; #define GAS __attribute__((address_space(1)))
; __device__ __forceinline__ void prep_seg(const bf16_t* QK, const float* cw, const size_t rowbase, const int t0, const int h, const int seg, const int lane, float (&o)[8][8]) {
;     const int rg = lane >> 3, cg = lane & 7, col = seg * 512 + h * 64 + cg * 8;
;     float wt[4][8];
; #pragma unroll
;     for (int j = 0; j < 4; ++j) { const f32x4 a = *(const GAS f32x4*)(cw + j * CONVD + col), b = *(const GAS f32x4*)(cw + j * CONVD + col + 4); wt[j][0] = a.x; wt[j][1] = a.y; wt[j][2] = a.z; wt[j][3] = a.w; wt[j][4] = b.x; wt[j][5] = b.y; wt[j][6] = b.z; wt[j][7] = b.w; }
; #pragma unroll
;     for (int r = 0; r < 8; ++r)
; #pragma unroll
;         for (int e = 0; e < 8; ++e) o[r][e] = 0.f;
	s_nop 0
	v_addc_co_u32_e32 v3, vcc, 0, v3, vcc
	global_load_dwordx4 v[4:7], v[2:3], off offset:2048
	s_nop 0
	global_load_dwordx4 v[0:3], v[0:1], off offset:16
	v_lshlrev_b32_e32 v160, 1, v67


; #define GAS __attribute__((address_space(1)))
; __device__ __forceinline__ void prep_seg(const bf16_t* QK, const float* cw, const size_t rowbase, const int t0, const int h, const int seg, const int lane, float (&o)[8][8]) {
;     ...
;     for (int rr = 0; rr < 11; ++rr) { const int t = t0 + 8 * rg + rr - 3; float x[8];
;         if (t >= 0) unpack8(*(const GAS v4u*)(QK + (rowbase + t) * CONVD + col), x); else {
; #pragma unroll
;             for (int e = 0; e < 8; ++e) x[e] = 0.f; }
	v_mov_b32_e32 v204, 0
	v_mov_b32_e32 v205, 0
	v_mov_b32_e32 v206, 0
	v_mov_b32_e32 v207, 0
	s_and_saveexec_b64 s[26:27], s[0:1]
	v_mov_b32_e32 v69, v65
	v_lshl_add_u64 v[68:69], s[82:83], 0, v[68:69]
	v_mov_b64_e32 v[124:125], s[46:47]
	v_mad_u64_u32 v[124:125], s[0:1], v68, s72, v[124:125]
	v_mad_i32_i24 v125, v69, s72, v125
	v_mov_b32_e32 v161, v65
	v_lshl_add_u64 v[68:69], v[124:125], 0, v[160:161]
	global_load_dwordx4 v[204:207], v[68:69], off
.LBB0_1048:
	s_or_b64 exec, exec, s[26:27]


; #define GAS __attribute__((address_space(1)))
; __device__ __forceinline__ void prep_seg(const bf16_t* QK, const float* cw, const size_t rowbase, const int t0, const int h, const int seg, const int lane, float (&o)[8][8]) {
;     ...
;     for (int rr = 0; rr < 11; ++rr) { const int t = t0 + 8 * rg + rr - 3; float x[8];
;         if (t >= 0) unpack8(*(const GAS v4u*)(QK + (rowbase + t) * CONVD + col), x); else {
; #pragma unroll
;             for (int e = 0; e < 8; ++e) x[e] = 0.f; }
	v_mov_b32_e32 v220, 0
	v_mov_b32_e32 v221, 0
	v_mov_b32_e32 v222, 0
	v_mov_b32_e32 v223, 0
	s_and_saveexec_b64 s[0:1], s[2:3]
	v_mov_b32_e32 v71, v65
	v_lshl_add_u64 v[68:69], s[82:83], 0, v[70:71]
	v_mov_b64_e32 v[70:71], s[46:47]
	v_mad_u64_u32 v[70:71], s[2:3], v68, s72, v[70:71]
	v_mad_i32_i24 v71, v69, s72, v71
	v_mov_b32_e32 v161, v65
	v_lshl_add_u64 v[68:69], v[70:71], 0, v[160:161]
	global_load_dwordx4 v[220:223], v[68:69], off
.LBB0_1050:
	s_or_b64 exec, exec, s[0:1]


; #define GAS __attribute__((address_space(1)))
; __device__ __forceinline__ void prep_seg(const bf16_t* QK, const float* cw, const size_t rowbase, const int t0, const int h, const int seg, const int lane, float (&o)[8][8]) {
;     ...
;     for (int rr = 0; rr < 11; ++rr) { const int t = t0 + 8 * rg + rr - 3; float x[8];
;         if (t >= 0) unpack8(*(const GAS v4u*)(QK + (rowbase + t) * CONVD + col), x); else {
; #pragma unroll
;             for (int e = 0; e < 8; ++e) x[e] = 0.f; }
	v_mov_b32_e32 v224, 0
	v_mov_b32_e32 v225, 0
	v_mov_b32_e32 v226, 0
	v_mov_b32_e32 v227, 0
	s_and_saveexec_b64 s[0:1], s[4:5]
	v_mov_b32_e32 v73, v65
	v_lshl_add_u64 v[70:71], s[82:83], 0, v[72:73]
	v_mov_b64_e32 v[72:73], s[46:47]
	v_mad_u64_u32 v[72:73], s[2:3], v70, s72, v[72:73]
	v_mad_i32_i24 v73, v71, s72, v73
	v_mov_b32_e32 v161, v65
	v_lshl_add_u64 v[70:71], v[72:73], 0, v[160:161]
	global_load_dwordx4 v[224:227], v[70:71], off
.LBB0_1052:
	s_or_b64 exec, exec, s[0:1]


; #define GAS __attribute__((address_space(1)))
; __device__ __forceinline__ void prep_seg(const bf16_t* QK, const float* cw, const size_t rowbase, const int t0, const int h, const int seg, const int lane, float (&o)[8][8]) {
;     ...
;     for (int rr = 0; rr < 11; ++rr) { const int t = t0 + 8 * rg + rr - 3; float x[8];
;         if (t >= 0) unpack8(*(const GAS v4u*)(QK + (rowbase + t) * CONVD + col), x); else {
; #pragma unroll
;             for (int e = 0; e < 8; ++e) x[e] = 0.f; }
	v_mov_b32_e32 v228, 0
	v_mov_b32_e32 v229, 0
	v_mov_b32_e32 v230, 0
	v_mov_b32_e32 v231, 0
	s_and_saveexec_b64 s[0:1], s[6:7]
	v_mov_b32_e32 v67, v65
	v_lshl_add_u64 v[66:67], s[82:83], 0, v[66:67]
	v_mov_b64_e32 v[70:71], s[46:47]
	v_mad_u64_u32 v[70:71], s[2:3], v66, s72, v[70:71]
	v_mad_i32_i24 v71, v67, s72, v71
	v_mov_b32_e32 v161, v65
	v_lshl_add_u64 v[66:67], v[70:71], 0, v[160:161]
	global_load_dwordx4 v[228:231], v[66:67], off
.LBB0_1054:
	s_or_b64 exec, exec, s[0:1]


; #define GAS __attribute__((address_space(1)))
; __device__ __forceinline__ void prep_seg(const bf16_t* QK, const float* cw, const size_t rowbase, const int t0, const int h, const int seg, const int lane, float (&o)[8][8]) {
;     ...
;     for (int rr = 0; rr < 11; ++rr) { const int t = t0 + 8 * rg + rr - 3; float x[8];
;         if (t >= 0) unpack8(*(const GAS v4u*)(QK + (rowbase + t) * CONVD + col), x); else {
; #pragma unroll
;             for (int e = 0; e < 8; ++e) x[e] = 0.f; }
	v_mov_b32_e32 v232, 0
	v_mov_b32_e32 v233, 0
	v_mov_b32_e32 v234, 0
	v_mov_b32_e32 v235, 0
	s_and_saveexec_b64 s[0:1], s[8:9]
	v_mov_b32_e32 v75, v65
	v_lshl_add_u64 v[66:67], s[82:83], 0, v[74:75]
	v_mov_b64_e32 v[70:71], s[46:47]
	v_mad_u64_u32 v[70:71], s[2:3], v66, s72, v[70:71]
	v_mad_i32_i24 v71, v67, s72, v71
	v_mov_b32_e32 v161, v65
	v_lshl_add_u64 v[66:67], v[70:71], 0, v[160:161]
	global_load_dwordx4 v[232:235], v[66:67], off
.LBB0_1056:
	s_or_b64 exec, exec, s[0:1]


; #define GAS __attribute__((address_space(1)))
; __device__ __forceinline__ void prep_seg(const bf16_t* QK, const float* cw, const size_t rowbase, const int t0, const int h, const int seg, const int lane, float (&o)[8][8]) {
;     ...
;     for (int rr = 0; rr < 11; ++rr) { const int t = t0 + 8 * rg + rr - 3; float x[8];
;         if (t >= 0) unpack8(*(const GAS v4u*)(QK + (rowbase + t) * CONVD + col), x); else {
; #pragma unroll
;             for (int e = 0; e < 8; ++e) x[e] = 0.f; }
	v_mov_b32_e32 v236, 0
	v_mov_b32_e32 v237, 0
	v_mov_b32_e32 v238, 0
	v_mov_b32_e32 v239, 0
	s_and_saveexec_b64 s[0:1], s[10:11]
	v_mov_b32_e32 v77, v65
	v_lshl_add_u64 v[66:67], s[82:83], 0, v[76:77]
	v_mov_b64_e32 v[70:71], s[46:47]
	v_mad_u64_u32 v[70:71], s[2:3], v66, s72, v[70:71]
	v_mad_i32_i24 v71, v67, s72, v71
	v_mov_b32_e32 v161, v65
	v_lshl_add_u64 v[66:67], v[70:71], 0, v[160:161]
	global_load_dwordx4 v[236:239], v[66:67], off
.LBB0_1058:
	s_or_b64 exec, exec, s[0:1]
	s_waitcnt vmcnt(5)
	v_lshlrev_b32_e32 v124, 16, v204
	v_and_b32_e32 v125, 0xffff0000, v204
	v_lshlrev_b32_e32 v126, 16, v205
	v_and_b32_e32 v127, 0xffff0000, v205
	v_lshlrev_b32_e32 v128, 16, v206
	v_and_b32_e32 v129, 0xffff0000, v206
	v_lshlrev_b32_e32 v130, 16, v207
	v_and_b32_e32 v131, 0xffff0000, v207
	s_waitcnt vmcnt(4)
	v_lshlrev_b32_e32 v88, 16, v220
	v_and_b32_e32 v89, 0xffff0000, v220
	v_lshlrev_b32_e32 v68, 16, v221
	v_and_b32_e32 v69, 0xffff0000, v221
	v_lshlrev_b32_e32 v132, 16, v222
	v_and_b32_e32 v133, 0xffff0000, v222
	v_lshlrev_b32_e32 v134, 16, v223
	v_and_b32_e32 v135, 0xffff0000, v223
	s_waitcnt vmcnt(3)
	v_lshlrev_b32_e32 v138, 16, v224
	v_and_b32_e32 v139, 0xffff0000, v224
	v_lshlrev_b32_e32 v140, 16, v225
	v_and_b32_e32 v141, 0xffff0000, v225
	v_lshlrev_b32_e32 v142, 16, v226
	v_and_b32_e32 v143, 0xffff0000, v226
	v_lshlrev_b32_e32 v144, 16, v227
	v_and_b32_e32 v145, 0xffff0000, v227
	s_waitcnt vmcnt(2)
	v_lshlrev_b32_e32 v136, 16, v228
	v_and_b32_e32 v137, 0xffff0000, v228
	v_lshlrev_b32_e32 v146, 16, v229
	v_and_b32_e32 v147, 0xffff0000, v229
	v_lshlrev_b32_e32 v148, 16, v230
	v_and_b32_e32 v149, 0xffff0000, v230
	v_lshlrev_b32_e32 v150, 16, v231
	v_and_b32_e32 v151, 0xffff0000, v231
	s_waitcnt vmcnt(1)
	v_lshlrev_b32_e32 v152, 16, v232
	v_and_b32_e32 v153, 0xffff0000, v232
	v_lshlrev_b32_e32 v154, 16, v233
	v_and_b32_e32 v155, 0xffff0000, v233
	v_lshlrev_b32_e32 v156, 16, v234
	v_and_b32_e32 v157, 0xffff0000, v234
	v_lshlrev_b32_e32 v158, 16, v235
	v_and_b32_e32 v159, 0xffff0000, v235
	s_waitcnt vmcnt(0)
	v_lshlrev_b32_e32 v162, 16, v236
	v_and_b32_e32 v163, 0xffff0000, v236
	v_lshlrev_b32_e32 v166, 16, v237
	v_and_b32_e32 v167, 0xffff0000, v237
	v_lshlrev_b32_e32 v168, 16, v238
	v_and_b32_e32 v169, 0xffff0000, v238
	v_lshlrev_b32_e32 v170, 16, v239
	v_and_b32_e32 v171, 0xffff0000, v239


; #define GAS __attribute__((address_space(1)))
; __device__ __forceinline__ void prep_seg(const bf16_t* QK, const float* cw, const size_t rowbase, const int t0, const int h, const int seg, const int lane, float (&o)[8][8]) {
;     ...
;     for (int rr = 0; rr < 11; ++rr) { const int t = t0 + 8 * rg + rr - 3; float x[8];
;         if (t >= 0) unpack8(*(const GAS v4u*)(QK + (rowbase + t) * CONVD + col), x); else {
; #pragma unroll
;             for (int e = 0; e < 8; ++e) x[e] = 0.f; }
	v_mov_b32_e32 v204, 0
	v_mov_b32_e32 v205, 0
	v_mov_b32_e32 v206, 0
	v_mov_b32_e32 v207, 0
	s_and_saveexec_b64 s[0:1], s[12:13]
	v_mov_b32_e32 v79, v65
	v_lshl_add_u64 v[66:67], s[82:83], 0, v[78:79]
	v_mov_b64_e32 v[70:71], s[46:47]
	v_mad_u64_u32 v[70:71], s[2:3], v66, s72, v[70:71]
	v_mad_i32_i24 v71, v67, s72, v71
	v_mov_b32_e32 v161, v65
	v_lshl_add_u64 v[66:67], v[70:71], 0, v[160:161]
	global_load_dwordx4 v[204:207], v[66:67], off
.LBB0_1060:
	s_or_b64 exec, exec, s[0:1]


; #define GAS __attribute__((address_space(1)))
; __device__ __forceinline__ void prep_seg(const bf16_t* QK, const float* cw, const size_t rowbase, const int t0, const int h, const int seg, const int lane, float (&o)[8][8]) {
;     ...
;     for (int rr = 0; rr < 11; ++rr) { const int t = t0 + 8 * rg + rr - 3; float x[8];
;         if (t >= 0) unpack8(*(const GAS v4u*)(QK + (rowbase + t) * CONVD + col), x); else {
; #pragma unroll
;             for (int e = 0; e < 8; ++e) x[e] = 0.f; }
	v_mov_b32_e32 v220, 0
	v_mov_b32_e32 v221, 0
	v_mov_b32_e32 v222, 0
	v_mov_b32_e32 v223, 0
	s_and_saveexec_b64 s[0:1], s[14:15]
	v_mov_b32_e32 v81, v65
	v_lshl_add_u64 v[66:67], s[82:83], 0, v[80:81]
	v_mov_b64_e32 v[70:71], s[46:47]
	v_mad_u64_u32 v[70:71], s[2:3], v66, s72, v[70:71]
	v_mad_i32_i24 v71, v67, s72, v71
	v_mov_b32_e32 v161, v65
	v_lshl_add_u64 v[66:67], v[70:71], 0, v[160:161]
	global_load_dwordx4 v[220:223], v[66:67], off
.LBB0_1062:
	s_or_b64 exec, exec, s[0:1]


; #define GAS __attribute__((address_space(1)))
; __device__ __forceinline__ void prep_seg(const bf16_t* QK, const float* cw, const size_t rowbase, const int t0, const int h, const int seg, const int lane, float (&o)[8][8]) {
;     ...
;     for (int rr = 0; rr < 11; ++rr) { const int t = t0 + 8 * rg + rr - 3; float x[8];
;         if (t >= 0) unpack8(*(const GAS v4u*)(QK + (rowbase + t) * CONVD + col), x); else {
; #pragma unroll
;             for (int e = 0; e < 8; ++e) x[e] = 0.f; }
	v_mov_b32_e32 v224, 0
	v_mov_b32_e32 v225, 0
	v_mov_b32_e32 v226, 0
	v_mov_b32_e32 v227, 0
	s_and_saveexec_b64 s[0:1], s[16:17]
	v_mov_b32_e32 v83, v65
	v_lshl_add_u64 v[66:67], s[82:83], 0, v[82:83]
	v_mov_b64_e32 v[70:71], s[46:47]
	v_mad_u64_u32 v[70:71], s[2:3], v66, s72, v[70:71]
	v_mad_i32_i24 v71, v67, s72, v71
	v_mov_b32_e32 v161, v65
	v_lshl_add_u64 v[66:67], v[70:71], 0, v[160:161]
	global_load_dwordx4 v[224:227], v[66:67], off
.LBB0_1064:
	s_or_b64 exec, exec, s[0:1]


; #define GAS __attribute__((address_space(1)))
; __device__ __forceinline__ void prep_seg(const bf16_t* QK, const float* cw, const size_t rowbase, const int t0, const int h, const int seg, const int lane, float (&o)[8][8]) {
;     ...
;     for (int rr = 0; rr < 11; ++rr) { const int t = t0 + 8 * rg + rr - 3; float x[8];
;         if (t >= 0) unpack8(*(const GAS v4u*)(QK + (rowbase + t) * CONVD + col), x); else {
; #pragma unroll
;             for (int e = 0; e < 8; ++e) x[e] = 0.f; }
	v_mov_b32_e32 v228, 0
	v_mov_b32_e32 v229, 0
	v_mov_b32_e32 v230, 0
	v_mov_b32_e32 v231, 0
	s_and_saveexec_b64 s[0:1], s[18:19]
	v_mov_b32_e32 v85, v65
	v_lshl_add_u64 v[66:67], s[82:83], 0, v[84:85]
	v_mov_b64_e32 v[70:71], s[46:47]
	v_mad_u64_u32 v[70:71], s[2:3], v66, s72, v[70:71]
	v_mad_i32_i24 v71, v67, s72, v71
	v_mov_b32_e32 v161, v65
	v_lshl_add_u64 v[66:67], v[70:71], 0, v[160:161]
	global_load_dwordx4 v[228:231], v[66:67], off
.LBB0_1066:
	s_or_b64 exec, exec, s[0:1]


; #define GAS __attribute__((address_space(1)))
; __device__ __forceinline__ void prep_seg(const bf16_t* QK, const float* cw, const size_t rowbase, const int t0, const int h, const int seg, const int lane, float (&o)[8][8]) {
;     ...
;     for (int rr = 0; rr < 11; ++rr) { const int t = t0 + 8 * rg + rr - 3; float x[8];
;         if (t >= 0) unpack8(*(const GAS v4u*)(QK + (rowbase + t) * CONVD + col), x); else {
; #pragma unroll
;             for (int e = 0; e < 8; ++e) x[e] = 0.f; }
	v_mov_b32_e32 v232, 0
	v_mov_b32_e32 v233, 0
	v_mov_b32_e32 v234, 0
	v_mov_b32_e32 v235, 0
	s_and_saveexec_b64 s[0:1], s[20:21]
	v_mov_b32_e32 v87, v65
	v_lshl_add_u64 v[66:67], s[82:83], 0, v[86:87]
	v_mov_b64_e32 v[70:71], s[46:47]
	v_mad_u64_u32 v[70:71], s[2:3], v66, s72, v[70:71]
	v_mad_i32_i24 v71, v67, s72, v71
	v_mov_b32_e32 v161, v65
	v_lshl_add_u64 v[66:67], v[70:71], 0, v[160:161]
	global_load_dwordx4 v[232:235], v[66:67], off
